# GEMM: accumulator clears moved from the tile head into the first K iteration, behind the 12 ds_read_b128 of the first phase (guarded by the loop counter)
# baseline (speedup 1.0000x reference)
; #define GM_WAIT_L(n) asm volatile("s_waitcnt lgkmcnt(" #n ")" ::: "memory")
; #define GM_BAR __builtin_amdgcn_s_barrier()
; #define GM_SCHED __builtin_amdgcn_sched_barrier(0)
; #define GM_LDA(dst, b, h) _Pragma("unroll") for (int m = 0; m < 4; ++m) _Pragma("unroll") for (int k = 0; k < 2; ++k) \
;         dst[m][k] = *(const LAS bf16x8*)(GM_SA(b, h) + aoff + (m * 2 + k) * 1024)
; #define GM_LDB(dst, b, h) _Pragma("unroll") for (int n = 0; n < 2; ++n) _Pragma("unroll") for (int k = 0; k < 2; ++k) \
;         dst[n][k] = *(const LAS bf16x8*)(GM_SB(b, h) + boff + (n * 2 + k) * 1024)
; #define GM_MMA(ai, bj, At, Bv) do { __builtin_amdgcn_s_setprio(1); \
;         _Pragma("unroll") for (int m = 0; m < 4; ++m) _Pragma("unroll") for (int n = 0; n < 2; ++n) _Pragma("unroll") for (int k = 0; k < 2; ++k) \
;             acc[ai][bj][m][n] = __builtin_amdgcn_mfma_f32_16x16x32_bf16(Bv[n][k], At[m][k], acc[ai][bj][m][n], 0, 0, 0); \
;         __builtin_amdgcn_s_setprio(0); } while (0)
; template <class Epi>
; __device__ __forceinline__ void gemm_phase(const bf16_t* __restrict__ A, const bf16_t* __restrict__ Bt, int M, int N, LAS unsigned char* lds, const Epi& epi, int vcu) {
;     ...
;         f32x4 acc[2][2][4][2];
; #pragma unroll
;         for (int a = 0; a < 2; ++a)
; #pragma unroll
;             for (int b = 0; b < 2; ++b)
; #pragma unroll
;                 for (int m = 0; m < 4; ++m)
; #pragma unroll
;                     for (int n = 0; n < 2; ++n) acc[a][b][m][n] = (f32x4){0.f, 0.f, 0.f, 0.f};
;         bf16x8 At[4][2], B0[2][2], B1[2][2];
;         for (int t = 0; t < NT; t += 2) {
;             const bool lastk = (t + 2 >= NT);
;             const int prow = lastk ? nrow : brow, pcol = lastk ? ncol : bcol, k2 = lastk ? 0 : t + 2, k3 = lastk ? 1 : t + 3;
;             GM_LDB(B0, 0, 0); GM_SCHED; GM_LDA(At, 0, 0); GM_STAGE(GM_SA(1, 1), A, brow + HALF, t + 1);
;             GM_WAIT_L(8); GM_BAR; GM_WAIT_L(0); GM_MMA(0, 0, At, B0); GM_BAR; GM_SCHED;
.LBB0_255:
	s_add_i32 s43, s43, 2
	v_add_u32_e32 v149, s88, v141
	s_cmp_gt_u32 s43, 13
	ds_read_b128 v[150:153], v149
	ds_read_b128 v[154:157], v149 offset:1024
	ds_read_b128 v[158:161], v149 offset:2048
	ds_read_b128 v[162:165], v149 offset:3072
	s_cselect_b64 s[54:55], -1, 0
	s_and_b64 s[54:55], s[54:55], exec
	s_cselect_b32 s54, 64, s45
	s_sub_i32 s10, s45, 64
	s_cmp_gt_u32 s43, 13
	s_cselect_b64 s[56:57], -1, 0
	s_and_b64 vcc, s[56:57], exec
	s_cselect_b32 s56, s5, s42
	s_cselect_b32 s58, s78, s44
	s_cselect_b32 s96, 0, s10
	v_add_u32_e32 v199, 0xc000, v133
	v_mov_b32_e32 v149, v1
	v_mov_b32_e32 v198, v130
	v_readfirstlane_b32 s10, v199
	ds_read_b128 v[166:169], v148
	ds_read_b128 v[170:173], v148 offset:1024
	ds_read_b128 v[174:177], v148 offset:2048
	ds_read_b128 v[178:181], v148 offset:3072
	ds_read_b128 v[182:185], v148 offset:4096
	ds_read_b128 v[186:189], v148 offset:5120
	ds_read_b128 v[190:193], v148 offset:6144
	ds_read_b128 v[194:197], v148 offset:7168
	s_mov_b32 m0, s10
	s_nop 0
	global_load_lds_dwordx4 v149, s[52:53]
	v_add_u32_e32 v149, 0xe000, v133
	s_nop 0
	v_readfirstlane_b32 s10, v149
	s_mov_b32 m0, s10
	s_nop 0
	global_load_lds_dwordx4 v198, s[52:53]
	s_cmp_lg_u32 s43, 0
	s_cbranch_scc1 .Lclr_skip0
	v_mov_b32_e32 v3, v2
	v_mov_b64_e32 v[4:5], 0
	v_mov_b64_e32 v[6:7], 0
	v_mov_b64_e32 v[8:9], 0
	v_mov_b64_e32 v[18:19], 0
	v_mov_b64_e32 v[20:21], 0
	v_mov_b64_e32 v[22:23], 0
	v_mov_b64_e32 v[24:25], 0
	v_mov_b64_e32 v[34:35], 0
	v_mov_b64_e32 v[36:37], 0
	v_mov_b64_e32 v[38:39], 0
	v_mov_b64_e32 v[40:41], 0
	v_mov_b64_e32 v[50:51], 0
	v_mov_b64_e32 v[52:53], 0
	v_mov_b64_e32 v[54:55], 0
	v_mov_b64_e32 v[56:57], 0
	v_mov_b64_e32 v[10:11], 0
	v_mov_b64_e32 v[12:13], 0
	v_mov_b64_e32 v[14:15], 0
	v_mov_b64_e32 v[16:17], 0
	v_mov_b64_e32 v[26:27], 0
	v_mov_b64_e32 v[28:29], 0
	v_mov_b64_e32 v[30:31], 0
	v_mov_b64_e32 v[32:33], 0
	v_mov_b64_e32 v[42:43], 0
	v_mov_b64_e32 v[44:45], 0
	v_mov_b64_e32 v[46:47], 0
	v_mov_b64_e32 v[48:49], 0
	v_mov_b64_e32 v[58:59], 0
	v_mov_b64_e32 v[60:61], 0
	v_mov_b64_e32 v[62:63], 0
	v_mov_b64_e32 v[64:65], 0
	v_mov_b64_e32 v[66:67], 0
	v_mov_b64_e32 v[68:69], 0
	v_mov_b64_e32 v[70:71], 0
	v_mov_b64_e32 v[72:73], 0
	v_mov_b64_e32 v[82:83], 0
	v_mov_b64_e32 v[84:85], 0
	v_mov_b64_e32 v[86:87], 0
	v_mov_b64_e32 v[88:89], 0
	v_mov_b64_e32 v[98:99], 0
	v_mov_b64_e32 v[100:101], 0
	v_mov_b64_e32 v[102:103], 0
	v_mov_b64_e32 v[104:105], 0
	v_mov_b64_e32 v[114:115], 0
	v_mov_b64_e32 v[116:117], 0
	v_mov_b64_e32 v[118:119], 0
	v_mov_b64_e32 v[120:121], 0
	v_mov_b64_e32 v[74:75], 0
	v_mov_b64_e32 v[76:77], 0
	v_mov_b64_e32 v[78:79], 0
	v_mov_b64_e32 v[80:81], 0
	v_mov_b64_e32 v[90:91], 0
	v_mov_b64_e32 v[92:93], 0
	v_mov_b64_e32 v[94:95], 0
	v_mov_b64_e32 v[96:97], 0
	v_mov_b64_e32 v[106:107], 0
	v_mov_b64_e32 v[108:109], 0
	v_mov_b64_e32 v[110:111], 0
	v_mov_b64_e32 v[112:113], 0
	v_mov_b64_e32 v[122:123], 0
	v_mov_b64_e32 v[124:125], 0
	v_mov_b64_e32 v[126:127], 0
	v_mov_b64_e32 v[128:129], 0
.Lclr_skip0:
	s_waitcnt lgkmcnt(8)
	s_barrier
	s_waitcnt lgkmcnt(0)
	s_setprio 1
	s_waitcnt lgkmcnt(0)
	v_mfma_f32_16x16x32_bf16 v[126:129], v[150:153], v[166:169], v[126:129]
	v_mfma_f32_16x16x32_bf16 v[122:125], v[158:161], v[166:169], v[122:125]
	v_mfma_f32_16x16x32_bf16 v[110:113], v[150:153], v[174:177], v[110:113]
	v_mfma_f32_16x16x32_bf16 v[106:109], v[158:161], v[174:177], v[106:109]
	v_mfma_f32_16x16x32_bf16 v[94:97], v[150:153], v[182:185], v[94:97]
	v_mfma_f32_16x16x32_bf16 v[90:93], v[158:161], v[182:185], v[90:93]
	v_mfma_f32_16x16x32_bf16 v[78:81], v[150:153], v[190:193], v[78:81]
	v_mfma_f32_16x16x32_bf16 v[74:77], v[158:161], v[190:193], v[74:77]
	v_mfma_f32_16x16x32_bf16 v[126:129], v[154:157], v[170:173], v[126:129]
	v_mfma_f32_16x16x32_bf16 v[122:125], v[162:165], v[170:173], v[122:125]
	v_mfma_f32_16x16x32_bf16 v[110:113], v[154:157], v[178:181], v[110:113]
	v_mfma_f32_16x16x32_bf16 v[106:109], v[162:165], v[178:181], v[106:109]
	v_mfma_f32_16x16x32_bf16 v[94:97], v[154:157], v[186:189], v[94:97]
	v_mfma_f32_16x16x32_bf16 v[90:93], v[162:165], v[186:189], v[90:93]
	v_mfma_f32_16x16x32_bf16 v[78:81], v[154:157], v[194:197], v[78:81]
	v_mfma_f32_16x16x32_bf16 v[74:77], v[162:165], v[194:197], v[74:77]
	s_setprio 0
	s_barrier
	s_ashr_i32 s59, s58, 31
	s_lshl_b64 s[58:59], s[58:59], 11
	s_add_u32 s2, s51, s58
	s_addc_u32 s83, s34, s59
	s_lshl_b64 s[58:59], s[96:97], 1
	v_add_u32_e32 v149, s89, v141
	s_add_u32 s10, s2, s58
	v_readfirstlane_b32 s55, v131
	ds_read_b128 v[198:201], v149
	ds_read_b128 v[202:205], v149 offset:1024
	ds_read_b128 v[212:215], v149 offset:2048
	ds_read_b128 v[216:219], v149 offset:3072
	s_addc_u32 s11, s83, s59
	v_mov_b32_e32 v149, v1
	v_mov_b32_e32 v208, v130
	s_mov_b32 m0, s55
	v_readfirstlane_b32 s55, v132
	s_nop 0
	global_load_lds_dwordx4 v149, s[10:11]
	s_mov_b32 m0, s55
	s_nop 0
	global_load_lds_dwordx4 v208, s[10:11]
	s_barrier
; #define GM_WAIT_V(n) asm volatile("s_waitcnt vmcnt(" #n ")" ::: "memory")
; #define GM_WAIT_L(n) asm volatile("s_waitcnt lgkmcnt(" #n ")" ::: "memory")
; #define GM_BAR __builtin_amdgcn_s_barrier()
; #define GM_SCHED __builtin_amdgcn_sched_barrier(0)
; #define GM_LDA(dst, b, h) _Pragma("unroll") for (int m = 0; m < 4; ++m) _Pragma("unroll") for (int k = 0; k < 2; ++k) \
;         dst[m][k] = *(const LAS bf16x8*)(GM_SA(b, h) + aoff + (m * 2 + k) * 1024)
; #define GM_LDB(dst, b, h) _Pragma("unroll") for (int n = 0; n < 2; ++n) _Pragma("unroll") for (int k = 0; k < 2; ++k) \
;         dst[n][k] = *(const LAS bf16x8*)(GM_SB(b, h) + boff + (n * 2 + k) * 1024)
; #define GM_MMA(ai, bj, At, Bv) do { __builtin_amdgcn_s_setprio(1); \
;         _Pragma("unroll") for (int m = 0; m < 4; ++m) _Pragma("unroll") for (int n = 0; n < 2; ++n) _Pragma("unroll") for (int k = 0; k < 2; ++k) \
;             acc[ai][bj][m][n] = __builtin_amdgcn_mfma_f32_16x16x32_bf16(Bv[n][k], At[m][k], acc[ai][bj][m][n], 0, 0, 0); \
;         __builtin_amdgcn_s_setprio(0); } while (0)
; template <class Epi>
; __device__ __forceinline__ void gemm_phase(const bf16_t* __restrict__ A, const bf16_t* __restrict__ Bt, int M, int N, LAS unsigned char* lds, const Epi& epi, int vcu) {
;     ...
;             GM_LDB(B1, 0, 1); GM_STAGE(GM_SB(0, 0), Bt, pcol, k2);
;             GM_BAR; GM_WAIT_L(0); GM_MMA(0, 1, At, B1); GM_BAR;
;             GM_LDA(At, 0, 1); GM_STAGE(GM_SA(0, 0), A, prow, k2);
;             GM_BAR; GM_WAIT_L(0); GM_MMA(1, 0, At, B0); GM_BAR; GM_SCHED;
;             GM_STAGE(GM_SB(0, 1), Bt, pcol + HALF, k2);
;             GM_WAIT_V(6); GM_BAR; GM_MMA(1, 1, At, B1); GM_BAR;
;             GM_LDB(B0, 1, 0); GM_SCHED; GM_LDA(At, 1, 0); GM_STAGE(GM_SA(0, 1), A, prow + HALF, k2);
;             GM_WAIT_L(8); GM_BAR; GM_WAIT_L(0); GM_MMA(0, 0, At, B0); GM_BAR; GM_SCHED;
	s_waitcnt lgkmcnt(0)
	s_setprio 1
	s_waitcnt lgkmcnt(0)
	v_mfma_f32_16x16x32_bf16 v[118:121], v[198:201], v[166:169], v[118:121]
	v_mfma_f32_16x16x32_bf16 v[114:117], v[212:215], v[166:169], v[114:117]
	v_mfma_f32_16x16x32_bf16 v[102:105], v[198:201], v[174:177], v[102:105]
	v_mfma_f32_16x16x32_bf16 v[98:101], v[212:215], v[174:177], v[98:101]
	v_mfma_f32_16x16x32_bf16 v[86:89], v[198:201], v[182:185], v[86:89]
	v_mfma_f32_16x16x32_bf16 v[82:85], v[212:215], v[182:185], v[82:85]
	v_mfma_f32_16x16x32_bf16 v[70:73], v[198:201], v[190:193], v[70:73]
	v_mfma_f32_16x16x32_bf16 v[66:69], v[212:215], v[190:193], v[66:69]
	v_mfma_f32_16x16x32_bf16 v[118:121], v[202:205], v[170:173], v[118:121]
	v_mfma_f32_16x16x32_bf16 v[114:117], v[216:219], v[170:173], v[114:117]
	v_mfma_f32_16x16x32_bf16 v[102:105], v[202:205], v[178:181], v[102:105]
	v_mfma_f32_16x16x32_bf16 v[98:101], v[216:219], v[178:181], v[98:101]
	v_mfma_f32_16x16x32_bf16 v[86:89], v[202:205], v[186:189], v[86:89]
	v_mfma_f32_16x16x32_bf16 v[82:85], v[216:219], v[186:189], v[82:85]
	v_mfma_f32_16x16x32_bf16 v[70:73], v[202:205], v[194:197], v[70:73]
	v_mfma_f32_16x16x32_bf16 v[66:69], v[216:219], v[194:197], v[66:69]
	s_setprio 0
	s_ashr_i32 s57, s56, 31
	s_lshl_b64 s[10:11], s[56:57], 11
	s_add_u32 s96, s14, s10
	s_addc_u32 s36, s15, s11
	s_add_u32 s10, s96, s58
	v_readfirstlane_b32 s55, v133
	s_addc_u32 s11, s36, s59
	v_mov_b32_e32 v149, v1
	v_mov_b32_e32 v208, v130
	s_mov_b32 m0, s55
	v_readfirstlane_b32 s55, v134
	s_barrier
	ds_read_b128 v[166:169], v148 offset:16384
	ds_read_b128 v[170:173], v148 offset:17408
	ds_read_b128 v[174:177], v148 offset:18432
	ds_read_b128 v[178:181], v148 offset:19456
	ds_read_b128 v[182:185], v148 offset:20480
	ds_read_b128 v[186:189], v148 offset:21504
	ds_read_b128 v[190:193], v148 offset:22528
	ds_read_b128 v[194:197], v148 offset:23552
	s_nop 0
	global_load_lds_dwordx4 v149, s[10:11]
	s_mov_b32 m0, s55
	s_nop 0
	global_load_lds_dwordx4 v208, s[10:11]
	s_barrier
	s_waitcnt lgkmcnt(0)
	s_setprio 1
	s_waitcnt lgkmcnt(0)
	v_mfma_f32_16x16x32_bf16 v[62:65], v[150:153], v[166:169], v[62:65]
	v_mfma_f32_16x16x32_bf16 v[58:61], v[158:161], v[166:169], v[58:61]
	v_mfma_f32_16x16x32_bf16 v[46:49], v[150:153], v[174:177], v[46:49]
	v_mfma_f32_16x16x32_bf16 v[42:45], v[158:161], v[174:177], v[42:45]
	v_mfma_f32_16x16x32_bf16 v[30:33], v[150:153], v[182:185], v[30:33]
	v_mfma_f32_16x16x32_bf16 v[26:29], v[158:161], v[182:185], v[26:29]
	v_mfma_f32_16x16x32_bf16 v[14:17], v[150:153], v[190:193], v[14:17]
	v_mfma_f32_16x16x32_bf16 v[10:13], v[158:161], v[190:193], v[10:13]
	v_mfma_f32_16x16x32_bf16 v[62:65], v[154:157], v[170:173], v[62:65]
	v_mfma_f32_16x16x32_bf16 v[58:61], v[162:165], v[170:173], v[58:61]
	v_mfma_f32_16x16x32_bf16 v[46:49], v[154:157], v[178:181], v[46:49]
	v_mfma_f32_16x16x32_bf16 v[42:45], v[162:165], v[178:181], v[42:45]
	v_mfma_f32_16x16x32_bf16 v[30:33], v[154:157], v[186:189], v[30:33]
	v_mfma_f32_16x16x32_bf16 v[26:29], v[162:165], v[186:189], v[26:29]
	v_mfma_f32_16x16x32_bf16 v[14:17], v[154:157], v[194:197], v[14:17]
	v_mfma_f32_16x16x32_bf16 v[10:13], v[162:165], v[194:197], v[10:13]
	s_setprio 0
	s_barrier
	s_add_u32 s35, s2, 0x40000
	s_addc_u32 s70, s83, 0
	s_add_u32 s56, s35, s58
	v_readfirstlane_b32 s55, v135
	s_addc_u32 s57, s70, s59
	v_mov_b32_e32 v149, v1
	v_mov_b32_e32 v150, v130
	s_mov_b32 m0, s55
	v_readfirstlane_b32 s55, v136
	s_nop 0
	global_load_lds_dwordx4 v149, s[56:57]
	s_mov_b32 m0, s55
	s_nop 0
	global_load_lds_dwordx4 v150, s[56:57]
	s_waitcnt vmcnt(6)
	s_barrier
	s_setprio 1
	v_mfma_f32_16x16x32_bf16 v[54:57], v[198:201], v[166:169], v[54:57]
	v_mfma_f32_16x16x32_bf16 v[50:53], v[212:215], v[166:169], v[50:53]
	v_mfma_f32_16x16x32_bf16 v[38:41], v[198:201], v[174:177], v[38:41]
	v_mfma_f32_16x16x32_bf16 v[34:37], v[212:215], v[174:177], v[34:37]
	v_mfma_f32_16x16x32_bf16 v[22:25], v[198:201], v[182:185], v[22:25]
	v_mfma_f32_16x16x32_bf16 v[18:21], v[212:215], v[182:185], v[18:21]
	v_mfma_f32_16x16x32_bf16 v[6:9], v[198:201], v[190:193], v[6:9]
	v_mfma_f32_16x16x32_bf16 v[2:5], v[212:215], v[190:193], v[2:5]
	v_mfma_f32_16x16x32_bf16 v[54:57], v[202:205], v[170:173], v[54:57]
	v_mfma_f32_16x16x32_bf16 v[50:53], v[216:219], v[170:173], v[50:53]
	v_mfma_f32_16x16x32_bf16 v[38:41], v[202:205], v[178:181], v[38:41]
	v_mfma_f32_16x16x32_bf16 v[34:37], v[216:219], v[178:181], v[34:37]
	v_mfma_f32_16x16x32_bf16 v[22:25], v[202:205], v[186:189], v[22:25]
	v_mfma_f32_16x16x32_bf16 v[18:21], v[216:219], v[186:189], v[18:21]
	v_mfma_f32_16x16x32_bf16 v[6:9], v[202:205], v[194:197], v[6:9]
	v_mfma_f32_16x16x32_bf16 v[2:5], v[216:219], v[194:197], v[2:5]
	s_setprio 0
	v_add_u32_e32 v149, s16, v141
	s_barrier
	ds_read_b128 v[150:153], v149
	ds_read_b128 v[154:157], v149 offset:1024
	ds_read_b128 v[158:161], v149 offset:2048
	ds_read_b128 v[162:165], v149 offset:3072
	s_add_u32 s10, s10, 0x40000
	v_readfirstlane_b32 s55, v137
	s_addc_u32 s11, s11, 0
	v_mov_b32_e32 v149, v1
	v_mov_b32_e32 v198, v130
	s_mov_b32 m0, s55
	v_readfirstlane_b32 s55, v138
	ds_read_b128 v[166:169], v148 offset:32768
	ds_read_b128 v[170:173], v148 offset:33792
	ds_read_b128 v[174:177], v148 offset:34816
	ds_read_b128 v[178:181], v148 offset:35840
	ds_read_b128 v[182:185], v148 offset:36864
	ds_read_b128 v[186:189], v148 offset:37888
	ds_read_b128 v[190:193], v148 offset:38912
	ds_read_b128 v[194:197], v148 offset:39936
	s_nop 0
	global_load_lds_dwordx4 v149, s[10:11]
	s_mov_b32 m0, s55
	s_nop 0
	global_load_lds_dwordx4 v198, s[10:11]
	s_waitcnt lgkmcnt(8)
	s_barrier
; #define GM_WAIT_L(n) asm volatile("s_waitcnt lgkmcnt(" #n ")" ::: "memory")
; #define GM_BAR __builtin_amdgcn_s_barrier()
; #define GM_SCHED __builtin_amdgcn_sched_barrier(0)
; #define GM_LDA(dst, b, h) _Pragma("unroll") for (int m = 0; m < 4; ++m) _Pragma("unroll") for (int k = 0; k < 2; ++k) \
;         dst[m][k] = *(const LAS bf16x8*)(GM_SA(b, h) + aoff + (m * 2 + k) * 1024)
; #define GM_LDB(dst, b, h) _Pragma("unroll") for (int n = 0; n < 2; ++n) _Pragma("unroll") for (int k = 0; k < 2; ++k) \
;         dst[n][k] = *(const LAS bf16x8*)(GM_SB(b, h) + boff + (n * 2 + k) * 1024)
; #define GM_MMA(ai, bj, At, Bv) do { __builtin_amdgcn_s_setprio(1); \
;         _Pragma("unroll") for (int m = 0; m < 4; ++m) _Pragma("unroll") for (int n = 0; n < 2; ++n) _Pragma("unroll") for (int k = 0; k < 2; ++k) \
;             acc[ai][bj][m][n] = __builtin_amdgcn_mfma_f32_16x16x32_bf16(Bv[n][k], At[m][k], acc[ai][bj][m][n], 0, 0, 0); \
;         __builtin_amdgcn_s_setprio(0); } while (0)
; template <class Epi>
; __device__ __forceinline__ void gemm_phase(const bf16_t* __restrict__ A, const bf16_t* __restrict__ Bt, int M, int N, LAS unsigned char* lds, const Epi& epi, int vcu) {
;     ...
;             GM_WAIT_L(8); GM_BAR; GM_WAIT_L(0); GM_MMA(0, 0, At, B0); GM_BAR; GM_SCHED;
;             GM_LDB(B1, 1, 1); GM_STAGE(GM_SB(1, 0), Bt, pcol, k3);
;             GM_BAR; GM_WAIT_L(0); GM_MMA(0, 1, At, B1); GM_BAR;
;             GM_LDA(At, 1, 1); GM_STAGE(GM_SA(1, 0), A, prow, k3);
;             GM_BAR; GM_WAIT_L(0); GM_MMA(1, 0, At, B0); GM_BAR; GM_SCHED;
	s_waitcnt lgkmcnt(0)
	s_setprio 1
	s_waitcnt lgkmcnt(0)
	v_mfma_f32_16x16x32_bf16 v[126:129], v[150:153], v[166:169], v[126:129]
	v_mfma_f32_16x16x32_bf16 v[122:125], v[158:161], v[166:169], v[122:125]
	v_mfma_f32_16x16x32_bf16 v[110:113], v[150:153], v[174:177], v[110:113]
	v_mfma_f32_16x16x32_bf16 v[106:109], v[158:161], v[174:177], v[106:109]
	v_mfma_f32_16x16x32_bf16 v[94:97], v[150:153], v[182:185], v[94:97]
	v_mfma_f32_16x16x32_bf16 v[90:93], v[158:161], v[182:185], v[90:93]
	v_mfma_f32_16x16x32_bf16 v[78:81], v[150:153], v[190:193], v[78:81]
	v_mfma_f32_16x16x32_bf16 v[74:77], v[158:161], v[190:193], v[74:77]
	v_mfma_f32_16x16x32_bf16 v[126:129], v[154:157], v[170:173], v[126:129]
	v_mfma_f32_16x16x32_bf16 v[122:125], v[162:165], v[170:173], v[122:125]
	v_mfma_f32_16x16x32_bf16 v[110:113], v[154:157], v[178:181], v[110:113]
	v_mfma_f32_16x16x32_bf16 v[106:109], v[162:165], v[178:181], v[106:109]
	v_mfma_f32_16x16x32_bf16 v[94:97], v[154:157], v[186:189], v[94:97]
	v_mfma_f32_16x16x32_bf16 v[90:93], v[162:165], v[186:189], v[90:93]
	v_mfma_f32_16x16x32_bf16 v[78:81], v[154:157], v[194:197], v[78:81]
	v_mfma_f32_16x16x32_bf16 v[74:77], v[162:165], v[194:197], v[74:77]
	s_setprio 0
	s_barrier
	s_mov_b32 s55, s97
	s_lshl_b64 s[10:11], s[54:55], 1
	v_add_u32_e32 v149, s17, v141
	s_add_u32 s54, s2, s10
	v_readfirstlane_b32 s2, v142
	ds_read_b128 v[198:201], v149
	ds_read_b128 v[202:205], v149 offset:1024
	ds_read_b128 v[212:215], v149 offset:2048
	ds_read_b128 v[216:219], v149 offset:3072
	s_addc_u32 s55, s83, s11
	v_mov_b32_e32 v149, v1
	v_mov_b32_e32 v208, v130
	s_mov_b32 m0, s2
	v_readfirstlane_b32 s2, v143
	s_nop 0
	global_load_lds_dwordx4 v149, s[54:55]
	s_mov_b32 m0, s2
	s_nop 0
	global_load_lds_dwordx4 v208, s[54:55]
	s_barrier
	s_waitcnt lgkmcnt(0)
	s_setprio 1
	s_waitcnt lgkmcnt(0)
	v_mfma_f32_16x16x32_bf16 v[118:121], v[198:201], v[166:169], v[118:121]
	v_mfma_f32_16x16x32_bf16 v[114:117], v[212:215], v[166:169], v[114:117]
	v_mfma_f32_16x16x32_bf16 v[102:105], v[198:201], v[174:177], v[102:105]
	v_mfma_f32_16x16x32_bf16 v[98:101], v[212:215], v[174:177], v[98:101]
	v_mfma_f32_16x16x32_bf16 v[86:89], v[198:201], v[182:185], v[86:89]
	v_mfma_f32_16x16x32_bf16 v[82:85], v[212:215], v[182:185], v[82:85]
	v_mfma_f32_16x16x32_bf16 v[70:73], v[198:201], v[190:193], v[70:73]
	v_mfma_f32_16x16x32_bf16 v[66:69], v[212:215], v[190:193], v[66:69]
	v_mfma_f32_16x16x32_bf16 v[118:121], v[202:205], v[170:173], v[118:121]
	v_mfma_f32_16x16x32_bf16 v[114:117], v[216:219], v[170:173], v[114:117]
	v_mfma_f32_16x16x32_bf16 v[102:105], v[202:205], v[178:181], v[102:105]
	v_mfma_f32_16x16x32_bf16 v[98:101], v[216:219], v[178:181], v[98:101]
	v_mfma_f32_16x16x32_bf16 v[86:89], v[202:205], v[186:189], v[86:89]
	v_mfma_f32_16x16x32_bf16 v[82:85], v[216:219], v[186:189], v[82:85]
	v_mfma_f32_16x16x32_bf16 v[70:73], v[202:205], v[194:197], v[70:73]
	v_mfma_f32_16x16x32_bf16 v[66:69], v[216:219], v[194:197], v[66:69]
	s_setprio 0
	s_add_u32 s54, s96, s10
	v_readfirstlane_b32 s2, v144
	s_addc_u32 s55, s36, s11
	v_mov_b32_e32 v149, v1
	v_mov_b32_e32 v208, v130
	s_mov_b32 m0, s2
	v_readfirstlane_b32 s2, v145
	s_barrier
	ds_read_b128 v[166:169], v148 offset:49152
	ds_read_b128 v[170:173], v148 offset:50176
	ds_read_b128 v[174:177], v148 offset:51200
	ds_read_b128 v[178:181], v148 offset:52224
	ds_read_b128 v[182:185], v148 offset:53248
	ds_read_b128 v[186:189], v148 offset:54272
	ds_read_b128 v[190:193], v148 offset:55296
	ds_read_b128 v[194:197], v148 offset:56320
	s_nop 0
	global_load_lds_dwordx4 v149, s[54:55]
	s_mov_b32 m0, s2
	s_nop 0
	global_load_lds_dwordx4 v208, s[54:55]
	s_barrier
; __device__ __forceinline__ unsigned pk_bf16(float lo, float hi) { const f32x2 v = {lo, hi}; const bf16v2 b = __builtin_convertvector(v, bf16v2); return __builtin_bit_cast(unsigned, b); }
; #define GM_WAIT_V(n) asm volatile("s_waitcnt vmcnt(" #n ")" ::: "memory")
; #define GM_WAIT_L(n) asm volatile("s_waitcnt lgkmcnt(" #n ")" ::: "memory")
; #define GM_BAR __builtin_amdgcn_s_barrier()
; #define GM_SCHED __builtin_amdgcn_sched_barrier(0)
; #define GM_MMA(ai, bj, At, Bv) do { __builtin_amdgcn_s_setprio(1); \
;         _Pragma("unroll") for (int m = 0; m < 4; ++m) _Pragma("unroll") for (int n = 0; n < 2; ++n) _Pragma("unroll") for (int k = 0; k < 2; ++k) \
;             acc[ai][bj][m][n] = __builtin_amdgcn_mfma_f32_16x16x32_bf16(Bv[n][k], At[m][k], acc[ai][bj][m][n], 0, 0, 0); \
;         __builtin_amdgcn_s_setprio(0); } while (0)
; template <class Epi>
; __device__ __forceinline__ void gemm_phase(const bf16_t* __restrict__ A, const bf16_t* __restrict__ Bt, int M, int N, LAS unsigned char* lds, const Epi& epi, int vcu) {
;     ...
;             GM_BAR; GM_WAIT_L(0); GM_MMA(1, 0, At, B0); GM_BAR; GM_SCHED;
;             GM_STAGE(GM_SB(1, 1), Bt, pcol + HALF, k3);
;             GM_WAIT_V(6); GM_BAR; GM_MMA(1, 1, At, B1); GM_BAR;
;         }
;     __device__ __forceinline__ void operator()(int row, int G, int fq, f32x4 v0, f32x4 v1) const {
;         const int col32 = G * 32;
;         const unsigned ro = (unsigned)row * (unsigned)ld;
;         if (col32 < rope_end) {
;             const int half = hd >> 1, hb = col32 & ~(hd - 1), d0 = ((col32 & (hd - 1)) >> 5) * 16 + fq * 4, pos = row & (SEQ - 1);
;             const unsigned to = (unsigned)(pos * half + d0);
;             const f32x4 c = *(const f32x4*)(cosT + to), s = *(const f32x4*)(sinT + to);
;             const f32x4 o1 = v0 * c - v1 * s, o2 = v1 * c + v0 * s;
;             u32x2 w1, w2; w1.x = pk_bf16(o1[0], o1[1]); w1.y = pk_bf16(o1[2], o1[3]); w2.x = pk_bf16(o2[0], o2[1]); w2.y = pk_bf16(o2[2], o2[3]);
;             *(u32x2*)(out + (ro + (unsigned)(hb + d0))) = w1; *(u32x2*)(out + (ro + (unsigned)(hb + half + d0))) = w2;
;         } else {
;             u32x4 w; w.x = pk_bf16(v0[0], v0[1]); w.y = pk_bf16(v0[2], v0[3]); w.z = pk_bf16(v1[0], v1[1]); w.w = pk_bf16(v1[2], v1[3]);
;             *(u32x4*)(out + (ro + (unsigned)(col32 + 8 * fq))) = w;
	s_waitcnt lgkmcnt(0)
	s_setprio 1
	s_waitcnt lgkmcnt(0)
	v_mfma_f32_16x16x32_bf16 v[62:65], v[150:153], v[166:169], v[62:65]
	v_mfma_f32_16x16x32_bf16 v[58:61], v[158:161], v[166:169], v[58:61]
	v_mfma_f32_16x16x32_bf16 v[46:49], v[150:153], v[174:177], v[46:49]
	v_mfma_f32_16x16x32_bf16 v[42:45], v[158:161], v[174:177], v[42:45]
	v_mfma_f32_16x16x32_bf16 v[30:33], v[150:153], v[182:185], v[30:33]
	v_mfma_f32_16x16x32_bf16 v[26:29], v[158:161], v[182:185], v[26:29]
	v_mfma_f32_16x16x32_bf16 v[14:17], v[150:153], v[190:193], v[14:17]
	v_mfma_f32_16x16x32_bf16 v[10:13], v[158:161], v[190:193], v[10:13]
	v_mfma_f32_16x16x32_bf16 v[62:65], v[154:157], v[170:173], v[62:65]
	v_mfma_f32_16x16x32_bf16 v[58:61], v[162:165], v[170:173], v[58:61]
	v_mfma_f32_16x16x32_bf16 v[46:49], v[154:157], v[178:181], v[46:49]
	v_mfma_f32_16x16x32_bf16 v[42:45], v[162:165], v[178:181], v[42:45]
	v_mfma_f32_16x16x32_bf16 v[30:33], v[154:157], v[186:189], v[30:33]
	v_mfma_f32_16x16x32_bf16 v[26:29], v[162:165], v[186:189], v[26:29]
	v_mfma_f32_16x16x32_bf16 v[14:17], v[154:157], v[194:197], v[14:17]
	v_mfma_f32_16x16x32_bf16 v[10:13], v[162:165], v[194:197], v[10:13]
	s_setprio 0
	s_barrier
	s_add_u32 s10, s35, s10
	v_readfirstlane_b32 s2, v146
	s_addc_u32 s11, s70, s11
	v_mov_b32_e32 v149, v1
	v_mov_b32_e32 v150, v130
	s_mov_b32 m0, s2
	v_readfirstlane_b32 s2, v147
	s_nop 0
	global_load_lds_dwordx4 v149, s[10:11]
	s_mov_b32 m0, s2
	s_nop 0
	global_load_lds_dwordx4 v150, s[10:11]
	s_waitcnt vmcnt(6)
	s_barrier
	s_setprio 1
	v_mfma_f32_16x16x32_bf16 v[54:57], v[198:201], v[166:169], v[54:57]
	v_mfma_f32_16x16x32_bf16 v[50:53], v[212:215], v[166:169], v[50:53]
	v_mfma_f32_16x16x32_bf16 v[38:41], v[198:201], v[174:177], v[38:41]
	v_mfma_f32_16x16x32_bf16 v[34:37], v[212:215], v[174:177], v[34:37]
	v_mfma_f32_16x16x32_bf16 v[22:25], v[198:201], v[182:185], v[22:25]
	v_mfma_f32_16x16x32_bf16 v[18:21], v[212:215], v[182:185], v[18:21]
	v_mfma_f32_16x16x32_bf16 v[6:9], v[198:201], v[190:193], v[6:9]
	v_mfma_f32_16x16x32_bf16 v[2:5], v[212:215], v[190:193], v[2:5]
	v_mfma_f32_16x16x32_bf16 v[54:57], v[202:205], v[170:173], v[54:57]
	v_mfma_f32_16x16x32_bf16 v[50:53], v[216:219], v[170:173], v[50:53]
	v_mfma_f32_16x16x32_bf16 v[38:41], v[202:205], v[178:181], v[38:41]
	v_mfma_f32_16x16x32_bf16 v[34:37], v[216:219], v[178:181], v[34:37]
	v_mfma_f32_16x16x32_bf16 v[22:25], v[202:205], v[186:189], v[22:25]
	v_mfma_f32_16x16x32_bf16 v[18:21], v[216:219], v[186:189], v[18:21]
	v_mfma_f32_16x16x32_bf16 v[6:9], v[202:205], v[194:197], v[6:9]
	v_mfma_f32_16x16x32_bf16 v[2:5], v[216:219], v[194:197], v[2:5]
	s_setprio 0
	s_addk_i32 s45, 0x80
	s_add_u32 s52, s52, 0x100
	s_addc_u32 s53, s53, 0
	s_barrier
	s_cbranch_vccz .LBB0_255
	s_cmp_lt_i32 s44, s21
	s_cbranch_scc1 .Lre_entry
	s_add_i32 s56, s44, s66
	s_add_i32 s10, s42, s65
	s_and_b32 s55, s56, 0xffffffe0
	v_mov_b32_e32 v149, v139
	v_mov_b32_e32 v150, v140
	s_cmp_ge_i32 s55, s21
	s_cselect_b64 s[42:43], -1, 0
	v_add_u32_e32 v151, s10, v149
	v_lshlrev_b32_e32 v149, 3, v150
	v_mul_lo_u32 v152, v151, s79
	s_mov_b64 s[44:45], -1
	s_and_b64 vcc, exec, s[42:43]
	s_cbranch_vccz .LBB0_258
	v_add3_u32 v158, v149, s55, v152
	v_mov_b32_e32 v159, v0
	v_cvt_pk_bf16_f32 v154, v126, v127
	v_cvt_pk_bf16_f32 v155, v128, v129
	v_cvt_pk_bf16_f32 v156, v122, v123
	v_cvt_pk_bf16_f32 v157, v124, v125
	v_lshl_add_u64 v[158:159], v[158:159], 1, s[76:77]
	global_store_dwordx4 v[158:159], v[154:157], off
	s_mov_b64 s[44:45], 0

; #define GM_WAIT_L(n) asm volatile("s_waitcnt lgkmcnt(" #n ")" ::: "memory")
; #define GM_BAR __builtin_amdgcn_s_barrier()
; #define GM_SCHED __builtin_amdgcn_sched_barrier(0)
; #define GM_LDA(dst, b, h) _Pragma("unroll") for (int m = 0; m < 4; ++m) _Pragma("unroll") for (int k = 0; k < 2; ++k) \
;         dst[m][k] = *(const LAS bf16x8*)(GM_SA(b, h) + aoff + (m * 2 + k) * 1024)
; #define GM_LDB(dst, b, h) _Pragma("unroll") for (int n = 0; n < 2; ++n) _Pragma("unroll") for (int k = 0; k < 2; ++k) \
;         dst[n][k] = *(const LAS bf16x8*)(GM_SB(b, h) + boff + (n * 2 + k) * 1024)
; #define GM_MMA(ai, bj, At, Bv) do { __builtin_amdgcn_s_setprio(1); \
;         _Pragma("unroll") for (int m = 0; m < 4; ++m) _Pragma("unroll") for (int n = 0; n < 2; ++n) _Pragma("unroll") for (int k = 0; k < 2; ++k) \
;             acc[ai][bj][m][n] = __builtin_amdgcn_mfma_f32_16x16x32_bf16(Bv[n][k], At[m][k], acc[ai][bj][m][n], 0, 0, 0); \
;         __builtin_amdgcn_s_setprio(0); } while (0)
; template <class Epi>
; __device__ __forceinline__ void gemm_phase(const bf16_t* __restrict__ A, const bf16_t* __restrict__ Bt, int M, int N, LAS unsigned char* lds, const Epi& epi, int vcu) {
;     ...
;         f32x4 acc[2][2][4][2];
; #pragma unroll
;         for (int a = 0; a < 2; ++a)
; #pragma unroll
;             for (int b = 0; b < 2; ++b)
; #pragma unroll
;                 for (int m = 0; m < 4; ++m)
; #pragma unroll
;                     for (int n = 0; n < 2; ++n) acc[a][b][m][n] = (f32x4){0.f, 0.f, 0.f, 0.f};
;         bf16x8 At[4][2], B0[2][2], B1[2][2];
;         for (int t = 0; t < NT; t += 2) {
;             const bool lastk = (t + 2 >= NT);
;             const int prow = lastk ? nrow : brow, pcol = lastk ? ncol : bcol, k2 = lastk ? 0 : t + 2, k3 = lastk ? 1 : t + 3;
;             GM_LDB(B0, 0, 0); GM_SCHED; GM_LDA(At, 0, 0); GM_STAGE(GM_SA(1, 1), A, brow + HALF, t + 1);
;             GM_WAIT_L(8); GM_BAR; GM_WAIT_L(0); GM_MMA(0, 0, At, B0); GM_BAR; GM_SCHED;
.LBB0_339:
	s_add_i32 s37, s37, 2
	v_add_u32_e32 v149, s88, v147
	s_cmp_gt_u32 s37, 13
	ds_read_b128 v[150:153], v149
	ds_read_b128 v[154:157], v149 offset:1024
	ds_read_b128 v[158:161], v149 offset:2048
	ds_read_b128 v[162:165], v149 offset:3072
	s_cselect_b64 s[48:49], -1, 0
	s_and_b64 s[48:49], s[48:49], exec
	s_cselect_b32 s48, 64, s43
	s_sub_i32 s10, s43, 64
	s_cmp_gt_u32 s37, 13
	s_cselect_b64 s[52:53], -1, 0
	s_and_b64 vcc, s[52:53], exec
	s_cselect_b32 s54, s29, s42
	s_cselect_b32 s52, s28, s44
	s_cselect_b32 s96, 0, s10
	v_add_u32_e32 v199, 0xc000, v133
	v_mov_b32_e32 v149, v130
	v_mov_b32_e32 v198, v1
	v_readfirstlane_b32 s10, v199
	ds_read_b128 v[166:169], v148
	ds_read_b128 v[170:173], v148 offset:1024
	ds_read_b128 v[174:177], v148 offset:2048
	ds_read_b128 v[178:181], v148 offset:3072
	ds_read_b128 v[182:185], v148 offset:4096
	ds_read_b128 v[186:189], v148 offset:5120
	ds_read_b128 v[190:193], v148 offset:6144
	ds_read_b128 v[194:197], v148 offset:7168
	s_mov_b32 m0, s10
	s_nop 0
	global_load_lds_dwordx4 v198, s[46:47]
	v_add_u32_e32 v198, 0xe000, v133
	s_nop 0
	v_readfirstlane_b32 s10, v198
	s_mov_b32 m0, s10
	s_nop 0
	global_load_lds_dwordx4 v149, s[46:47]
	s_cmp_lg_u32 s37, 0
	s_cbranch_scc1 .Lclr_skip1
	v_mov_b32_e32 v3, v2
	v_mov_b64_e32 v[4:5], 0
	v_mov_b64_e32 v[6:7], 0
	v_mov_b64_e32 v[8:9], 0
	v_mov_b64_e32 v[18:19], 0
	v_mov_b64_e32 v[20:21], 0
	v_mov_b64_e32 v[22:23], 0
	v_mov_b64_e32 v[24:25], 0
	v_mov_b64_e32 v[34:35], 0
	v_mov_b64_e32 v[36:37], 0
	v_mov_b64_e32 v[38:39], 0
	v_mov_b64_e32 v[40:41], 0
	v_mov_b64_e32 v[50:51], 0
	v_mov_b64_e32 v[52:53], 0
	v_mov_b64_e32 v[54:55], 0
	v_mov_b64_e32 v[56:57], 0
	v_mov_b64_e32 v[10:11], 0
	v_mov_b64_e32 v[12:13], 0
	v_mov_b64_e32 v[14:15], 0
	v_mov_b64_e32 v[16:17], 0
	v_mov_b64_e32 v[26:27], 0
	v_mov_b64_e32 v[28:29], 0
	v_mov_b64_e32 v[30:31], 0
	v_mov_b64_e32 v[32:33], 0
	v_mov_b64_e32 v[42:43], 0
	v_mov_b64_e32 v[44:45], 0
	v_mov_b64_e32 v[46:47], 0
	v_mov_b64_e32 v[48:49], 0
	v_mov_b64_e32 v[58:59], 0
	v_mov_b64_e32 v[60:61], 0
	v_mov_b64_e32 v[62:63], 0
	v_mov_b64_e32 v[64:65], 0
	v_mov_b64_e32 v[66:67], 0
	v_mov_b64_e32 v[68:69], 0
	v_mov_b64_e32 v[70:71], 0
	v_mov_b64_e32 v[72:73], 0
	v_mov_b64_e32 v[82:83], 0
	v_mov_b64_e32 v[84:85], 0
	v_mov_b64_e32 v[86:87], 0
	v_mov_b64_e32 v[88:89], 0
	v_mov_b64_e32 v[98:99], 0
	v_mov_b64_e32 v[100:101], 0
	v_mov_b64_e32 v[102:103], 0
	v_mov_b64_e32 v[104:105], 0
	v_mov_b64_e32 v[114:115], 0
	v_mov_b64_e32 v[116:117], 0
	v_mov_b64_e32 v[118:119], 0
	v_mov_b64_e32 v[120:121], 0
	v_mov_b64_e32 v[74:75], 0
	v_mov_b64_e32 v[76:77], 0
	v_mov_b64_e32 v[78:79], 0
	v_mov_b64_e32 v[80:81], 0
	v_mov_b64_e32 v[90:91], 0
	v_mov_b64_e32 v[92:93], 0
	v_mov_b64_e32 v[94:95], 0
	v_mov_b64_e32 v[96:97], 0
	v_mov_b64_e32 v[106:107], 0
	v_mov_b64_e32 v[108:109], 0
	v_mov_b64_e32 v[110:111], 0
	v_mov_b64_e32 v[112:113], 0
	v_mov_b64_e32 v[122:123], 0
	v_mov_b64_e32 v[124:125], 0
	v_mov_b64_e32 v[126:127], 0
	v_mov_b64_e32 v[128:129], 0
.Lclr_skip1:
	s_waitcnt lgkmcnt(8)
	s_barrier
	s_waitcnt lgkmcnt(0)
	s_setprio 1
	s_waitcnt lgkmcnt(0)
	v_mfma_f32_16x16x32_bf16 v[126:129], v[150:153], v[166:169], v[126:129]
	v_mfma_f32_16x16x32_bf16 v[122:125], v[158:161], v[166:169], v[122:125]
	v_mfma_f32_16x16x32_bf16 v[110:113], v[150:153], v[174:177], v[110:113]
	v_mfma_f32_16x16x32_bf16 v[106:109], v[158:161], v[174:177], v[106:109]
	v_mfma_f32_16x16x32_bf16 v[94:97], v[150:153], v[182:185], v[94:97]
	v_mfma_f32_16x16x32_bf16 v[90:93], v[158:161], v[182:185], v[90:93]
	v_mfma_f32_16x16x32_bf16 v[78:81], v[150:153], v[190:193], v[78:81]
	v_mfma_f32_16x16x32_bf16 v[74:77], v[158:161], v[190:193], v[74:77]
	v_mfma_f32_16x16x32_bf16 v[126:129], v[154:157], v[170:173], v[126:129]
	v_mfma_f32_16x16x32_bf16 v[122:125], v[162:165], v[170:173], v[122:125]
	v_mfma_f32_16x16x32_bf16 v[110:113], v[154:157], v[178:181], v[110:113]
	v_mfma_f32_16x16x32_bf16 v[106:109], v[162:165], v[178:181], v[106:109]
	v_mfma_f32_16x16x32_bf16 v[94:97], v[154:157], v[186:189], v[94:97]
	v_mfma_f32_16x16x32_bf16 v[90:93], v[162:165], v[186:189], v[90:93]
	v_mfma_f32_16x16x32_bf16 v[78:81], v[154:157], v[194:197], v[78:81]
	v_mfma_f32_16x16x32_bf16 v[74:77], v[162:165], v[194:197], v[74:77]
	s_setprio 0
	s_barrier
	s_ashr_i32 s53, s52, 31
	s_lshl_b64 s[56:57], s[52:53], 11
	s_add_u32 s10, s25, s56
	s_addc_u32 s11, s34, s57
	s_lshl_b64 s[56:57], s[96:97], 1
	v_add_u32_e32 v149, s89, v147
	s_add_u32 s64, s10, s56
	v_readfirstlane_b32 s45, v131
	ds_read_b128 v[198:201], v149
	ds_read_b128 v[202:205], v149 offset:1024
	ds_read_b128 v[212:215], v149 offset:2048
	ds_read_b128 v[216:219], v149 offset:3072
	s_addc_u32 s65, s11, s57
	v_mov_b32_e32 v149, v130
	v_mov_b32_e32 v208, v1
	s_mov_b32 m0, s45
	v_readfirstlane_b32 s45, v132
	s_nop 0
	global_load_lds_dwordx4 v208, s[64:65]
	s_mov_b32 m0, s45
	s_nop 0
	global_load_lds_dwordx4 v149, s[64:65]
	s_barrier
; #define GM_WAIT_V(n) asm volatile("s_waitcnt vmcnt(" #n ")" ::: "memory")
; #define GM_WAIT_L(n) asm volatile("s_waitcnt lgkmcnt(" #n ")" ::: "memory")
; #define GM_BAR __builtin_amdgcn_s_barrier()
; #define GM_SCHED __builtin_amdgcn_sched_barrier(0)
; #define GM_LDA(dst, b, h) _Pragma("unroll") for (int m = 0; m < 4; ++m) _Pragma("unroll") for (int k = 0; k < 2; ++k) \
;         dst[m][k] = *(const LAS bf16x8*)(GM_SA(b, h) + aoff + (m * 2 + k) * 1024)
; #define GM_LDB(dst, b, h) _Pragma("unroll") for (int n = 0; n < 2; ++n) _Pragma("unroll") for (int k = 0; k < 2; ++k) \
;         dst[n][k] = *(const LAS bf16x8*)(GM_SB(b, h) + boff + (n * 2 + k) * 1024)
; #define GM_MMA(ai, bj, At, Bv) do { __builtin_amdgcn_s_setprio(1); \
;         _Pragma("unroll") for (int m = 0; m < 4; ++m) _Pragma("unroll") for (int n = 0; n < 2; ++n) _Pragma("unroll") for (int k = 0; k < 2; ++k) \
;             acc[ai][bj][m][n] = __builtin_amdgcn_mfma_f32_16x16x32_bf16(Bv[n][k], At[m][k], acc[ai][bj][m][n], 0, 0, 0); \
;         __builtin_amdgcn_s_setprio(0); } while (0)
; template <class Epi>
; __device__ __forceinline__ void gemm_phase(const bf16_t* __restrict__ A, const bf16_t* __restrict__ Bt, int M, int N, LAS unsigned char* lds, const Epi& epi, int vcu) {
;     ...
;             GM_LDB(B1, 0, 1); GM_STAGE(GM_SB(0, 0), Bt, pcol, k2);
;             GM_BAR; GM_WAIT_L(0); GM_MMA(0, 1, At, B1); GM_BAR;
;             GM_LDA(At, 0, 1); GM_STAGE(GM_SA(0, 0), A, prow, k2);
;             GM_BAR; GM_WAIT_L(0); GM_MMA(1, 0, At, B0); GM_BAR; GM_SCHED;
;             GM_STAGE(GM_SB(0, 1), Bt, pcol + HALF, k2);
;             GM_WAIT_V(6); GM_BAR; GM_MMA(1, 1, At, B1); GM_BAR;
;             GM_LDB(B0, 1, 0); GM_SCHED; GM_LDA(At, 1, 0); GM_STAGE(GM_SA(0, 1), A, prow + HALF, k2);
;             GM_WAIT_L(8); GM_BAR; GM_WAIT_L(0); GM_MMA(0, 0, At, B0); GM_BAR; GM_SCHED;
	s_waitcnt lgkmcnt(0)
	s_setprio 1
	s_waitcnt lgkmcnt(0)
	v_mfma_f32_16x16x32_bf16 v[118:121], v[198:201], v[166:169], v[118:121]
	v_mfma_f32_16x16x32_bf16 v[114:117], v[212:215], v[166:169], v[114:117]
	v_mfma_f32_16x16x32_bf16 v[102:105], v[198:201], v[174:177], v[102:105]
	v_mfma_f32_16x16x32_bf16 v[98:101], v[212:215], v[174:177], v[98:101]
	v_mfma_f32_16x16x32_bf16 v[86:89], v[198:201], v[182:185], v[86:89]
	v_mfma_f32_16x16x32_bf16 v[82:85], v[212:215], v[182:185], v[82:85]
	v_mfma_f32_16x16x32_bf16 v[70:73], v[198:201], v[190:193], v[70:73]
	v_mfma_f32_16x16x32_bf16 v[66:69], v[212:215], v[190:193], v[66:69]
	v_mfma_f32_16x16x32_bf16 v[118:121], v[202:205], v[170:173], v[118:121]
	v_mfma_f32_16x16x32_bf16 v[114:117], v[216:219], v[170:173], v[114:117]
	v_mfma_f32_16x16x32_bf16 v[102:105], v[202:205], v[178:181], v[102:105]
	v_mfma_f32_16x16x32_bf16 v[98:101], v[216:219], v[178:181], v[98:101]
	v_mfma_f32_16x16x32_bf16 v[86:89], v[202:205], v[186:189], v[86:89]
	v_mfma_f32_16x16x32_bf16 v[82:85], v[216:219], v[186:189], v[82:85]
	v_mfma_f32_16x16x32_bf16 v[70:73], v[202:205], v[194:197], v[70:73]
	v_mfma_f32_16x16x32_bf16 v[66:69], v[216:219], v[194:197], v[66:69]
	s_setprio 0
	s_ashr_i32 s55, s54, 31
	s_lshl_b64 s[54:55], s[54:55], 11
	s_add_u32 s45, s74, s54
	s_addc_u32 s51, s75, s55
	s_add_u32 s54, s45, s56
	v_readfirstlane_b32 s49, v133
	s_addc_u32 s55, s51, s57
	v_mov_b32_e32 v149, v130
	v_mov_b32_e32 v208, v1
	s_mov_b32 m0, s49
	v_readfirstlane_b32 s49, v134
	s_barrier
	ds_read_b128 v[166:169], v148 offset:16384
	ds_read_b128 v[170:173], v148 offset:17408
	ds_read_b128 v[174:177], v148 offset:18432
	ds_read_b128 v[178:181], v148 offset:19456
	ds_read_b128 v[182:185], v148 offset:20480
	ds_read_b128 v[186:189], v148 offset:21504
	ds_read_b128 v[190:193], v148 offset:22528
	ds_read_b128 v[194:197], v148 offset:23552
	s_nop 0
	global_load_lds_dwordx4 v208, s[54:55]
	s_mov_b32 m0, s49
	s_nop 0
	global_load_lds_dwordx4 v149, s[54:55]
	s_barrier
	s_waitcnt lgkmcnt(0)
	s_setprio 1
	s_waitcnt lgkmcnt(0)
	v_mfma_f32_16x16x32_bf16 v[62:65], v[150:153], v[166:169], v[62:65]
	v_mfma_f32_16x16x32_bf16 v[58:61], v[158:161], v[166:169], v[58:61]
	v_mfma_f32_16x16x32_bf16 v[46:49], v[150:153], v[174:177], v[46:49]
	v_mfma_f32_16x16x32_bf16 v[42:45], v[158:161], v[174:177], v[42:45]
	v_mfma_f32_16x16x32_bf16 v[30:33], v[150:153], v[182:185], v[30:33]
	v_mfma_f32_16x16x32_bf16 v[26:29], v[158:161], v[182:185], v[26:29]
	v_mfma_f32_16x16x32_bf16 v[14:17], v[150:153], v[190:193], v[14:17]
	v_mfma_f32_16x16x32_bf16 v[10:13], v[158:161], v[190:193], v[10:13]
	v_mfma_f32_16x16x32_bf16 v[62:65], v[154:157], v[170:173], v[62:65]
	v_mfma_f32_16x16x32_bf16 v[58:61], v[162:165], v[170:173], v[58:61]
	v_mfma_f32_16x16x32_bf16 v[46:49], v[154:157], v[178:181], v[46:49]
	v_mfma_f32_16x16x32_bf16 v[42:45], v[162:165], v[178:181], v[42:45]
	v_mfma_f32_16x16x32_bf16 v[30:33], v[154:157], v[186:189], v[30:33]
	v_mfma_f32_16x16x32_bf16 v[26:29], v[162:165], v[186:189], v[26:29]
	v_mfma_f32_16x16x32_bf16 v[14:17], v[154:157], v[194:197], v[14:17]
	v_mfma_f32_16x16x32_bf16 v[10:13], v[162:165], v[194:197], v[10:13]
	s_setprio 0
	s_barrier
	s_bitset1_b32 s52, 7
	s_ashr_i32 s53, s52, 31
	s_lshl_b64 s[52:53], s[52:53], 11
	s_add_u32 s58, s25, s52
	s_addc_u32 s59, s34, s53
	s_add_u32 s52, s58, s56
	v_readfirstlane_b32 s49, v135
	s_addc_u32 s53, s59, s57
	v_mov_b32_e32 v149, v130
	v_mov_b32_e32 v150, v1
	s_mov_b32 m0, s49
	v_readfirstlane_b32 s49, v136
	s_nop 0
	global_load_lds_dwordx4 v150, s[52:53]
	s_mov_b32 m0, s49
	s_nop 0
	global_load_lds_dwordx4 v149, s[52:53]
	s_waitcnt vmcnt(6)
	s_barrier
	s_setprio 1
	v_mfma_f32_16x16x32_bf16 v[54:57], v[198:201], v[166:169], v[54:57]
	v_mfma_f32_16x16x32_bf16 v[50:53], v[212:215], v[166:169], v[50:53]
	v_mfma_f32_16x16x32_bf16 v[38:41], v[198:201], v[174:177], v[38:41]
	v_mfma_f32_16x16x32_bf16 v[34:37], v[212:215], v[174:177], v[34:37]
	v_mfma_f32_16x16x32_bf16 v[22:25], v[198:201], v[182:185], v[22:25]
	v_mfma_f32_16x16x32_bf16 v[18:21], v[212:215], v[182:185], v[18:21]
	v_mfma_f32_16x16x32_bf16 v[6:9], v[198:201], v[190:193], v[6:9]
	v_mfma_f32_16x16x32_bf16 v[2:5], v[212:215], v[190:193], v[2:5]
	v_mfma_f32_16x16x32_bf16 v[54:57], v[202:205], v[170:173], v[54:57]
	v_mfma_f32_16x16x32_bf16 v[50:53], v[216:219], v[170:173], v[50:53]
	v_mfma_f32_16x16x32_bf16 v[38:41], v[202:205], v[178:181], v[38:41]
	v_mfma_f32_16x16x32_bf16 v[34:37], v[216:219], v[178:181], v[34:37]
	v_mfma_f32_16x16x32_bf16 v[22:25], v[202:205], v[186:189], v[22:25]
	v_mfma_f32_16x16x32_bf16 v[18:21], v[216:219], v[186:189], v[18:21]
	v_mfma_f32_16x16x32_bf16 v[6:9], v[202:205], v[194:197], v[6:9]
	v_mfma_f32_16x16x32_bf16 v[2:5], v[216:219], v[194:197], v[2:5]
	s_setprio 0
	v_add_u32_e32 v149, s16, v147
	s_barrier
	ds_read_b128 v[150:153], v149
	ds_read_b128 v[154:157], v149 offset:1024
	ds_read_b128 v[158:161], v149 offset:2048
	ds_read_b128 v[162:165], v149 offset:3072
	s_add_u32 s52, s54, 0x40000
	v_readfirstlane_b32 s49, v137
	s_addc_u32 s53, s55, 0
	v_mov_b32_e32 v149, v130
	v_mov_b32_e32 v198, v1
	s_mov_b32 m0, s49
	v_readfirstlane_b32 s49, v138
	ds_read_b128 v[166:169], v148 offset:32768
	ds_read_b128 v[170:173], v148 offset:33792
	ds_read_b128 v[174:177], v148 offset:34816
	ds_read_b128 v[178:181], v148 offset:35840
	ds_read_b128 v[182:185], v148 offset:36864
	ds_read_b128 v[186:189], v148 offset:37888
	ds_read_b128 v[190:193], v148 offset:38912
	ds_read_b128 v[194:197], v148 offset:39936
	s_nop 0
	global_load_lds_dwordx4 v198, s[52:53]
	s_mov_b32 m0, s49
	s_nop 0
	global_load_lds_dwordx4 v149, s[52:53]
	s_waitcnt lgkmcnt(8)
	s_barrier
; #define GM_WAIT_L(n) asm volatile("s_waitcnt lgkmcnt(" #n ")" ::: "memory")
; #define GM_BAR __builtin_amdgcn_s_barrier()
; #define GM_SCHED __builtin_amdgcn_sched_barrier(0)
; #define GM_LDA(dst, b, h) _Pragma("unroll") for (int m = 0; m < 4; ++m) _Pragma("unroll") for (int k = 0; k < 2; ++k) \
;         dst[m][k] = *(const LAS bf16x8*)(GM_SA(b, h) + aoff + (m * 2 + k) * 1024)
; #define GM_LDB(dst, b, h) _Pragma("unroll") for (int n = 0; n < 2; ++n) _Pragma("unroll") for (int k = 0; k < 2; ++k) \
;         dst[n][k] = *(const LAS bf16x8*)(GM_SB(b, h) + boff + (n * 2 + k) * 1024)
; #define GM_MMA(ai, bj, At, Bv) do { __builtin_amdgcn_s_setprio(1); \
;         _Pragma("unroll") for (int m = 0; m < 4; ++m) _Pragma("unroll") for (int n = 0; n < 2; ++n) _Pragma("unroll") for (int k = 0; k < 2; ++k) \
;             acc[ai][bj][m][n] = __builtin_amdgcn_mfma_f32_16x16x32_bf16(Bv[n][k], At[m][k], acc[ai][bj][m][n], 0, 0, 0); \
;         __builtin_amdgcn_s_setprio(0); } while (0)
; template <class Epi>
; __device__ __forceinline__ void gemm_phase(const bf16_t* __restrict__ A, const bf16_t* __restrict__ Bt, int M, int N, LAS unsigned char* lds, const Epi& epi, int vcu) {
;     ...
;             GM_WAIT_L(8); GM_BAR; GM_WAIT_L(0); GM_MMA(0, 0, At, B0); GM_BAR; GM_SCHED;
;             GM_LDB(B1, 1, 1); GM_STAGE(GM_SB(1, 0), Bt, pcol, k3);
;             GM_BAR; GM_WAIT_L(0); GM_MMA(0, 1, At, B1); GM_BAR;
;             GM_LDA(At, 1, 1); GM_STAGE(GM_SA(1, 0), A, prow, k3);
;             GM_BAR; GM_WAIT_L(0); GM_MMA(1, 0, At, B0); GM_BAR; GM_SCHED;
	s_waitcnt lgkmcnt(0)
	s_setprio 1
	s_waitcnt lgkmcnt(0)
	v_mfma_f32_16x16x32_bf16 v[126:129], v[150:153], v[166:169], v[126:129]
	v_mfma_f32_16x16x32_bf16 v[122:125], v[158:161], v[166:169], v[122:125]
	v_mfma_f32_16x16x32_bf16 v[110:113], v[150:153], v[174:177], v[110:113]
	v_mfma_f32_16x16x32_bf16 v[106:109], v[158:161], v[174:177], v[106:109]
	v_mfma_f32_16x16x32_bf16 v[94:97], v[150:153], v[182:185], v[94:97]
	v_mfma_f32_16x16x32_bf16 v[90:93], v[158:161], v[182:185], v[90:93]
	v_mfma_f32_16x16x32_bf16 v[78:81], v[150:153], v[190:193], v[78:81]
	v_mfma_f32_16x16x32_bf16 v[74:77], v[158:161], v[190:193], v[74:77]
	v_mfma_f32_16x16x32_bf16 v[126:129], v[154:157], v[170:173], v[126:129]
	v_mfma_f32_16x16x32_bf16 v[122:125], v[162:165], v[170:173], v[122:125]
	v_mfma_f32_16x16x32_bf16 v[110:113], v[154:157], v[178:181], v[110:113]
	v_mfma_f32_16x16x32_bf16 v[106:109], v[162:165], v[178:181], v[106:109]
	v_mfma_f32_16x16x32_bf16 v[94:97], v[154:157], v[186:189], v[94:97]
	v_mfma_f32_16x16x32_bf16 v[90:93], v[162:165], v[186:189], v[90:93]
	v_mfma_f32_16x16x32_bf16 v[78:81], v[154:157], v[194:197], v[78:81]
	v_mfma_f32_16x16x32_bf16 v[74:77], v[162:165], v[194:197], v[74:77]
	s_setprio 0
	s_barrier
	s_mov_b32 s49, s97
	s_lshl_b64 s[48:49], s[48:49], 1
	v_add_u32_e32 v149, s17, v147
	s_add_u32 s52, s10, s48
	v_readfirstlane_b32 s10, v139
	ds_read_b128 v[198:201], v149
	ds_read_b128 v[202:205], v149 offset:1024
	ds_read_b128 v[212:215], v149 offset:2048
	ds_read_b128 v[216:219], v149 offset:3072
	s_addc_u32 s53, s11, s49
	v_mov_b32_e32 v149, v130
	v_mov_b32_e32 v208, v1
	s_mov_b32 m0, s10
	v_readfirstlane_b32 s10, v140
	s_nop 0
	global_load_lds_dwordx4 v208, s[52:53]
	s_mov_b32 m0, s10
	s_nop 0
	global_load_lds_dwordx4 v149, s[52:53]
	s_barrier
	s_waitcnt lgkmcnt(0)
	s_setprio 1
	s_waitcnt lgkmcnt(0)
	v_mfma_f32_16x16x32_bf16 v[118:121], v[198:201], v[166:169], v[118:121]
	v_mfma_f32_16x16x32_bf16 v[114:117], v[212:215], v[166:169], v[114:117]
	v_mfma_f32_16x16x32_bf16 v[102:105], v[198:201], v[174:177], v[102:105]
	v_mfma_f32_16x16x32_bf16 v[98:101], v[212:215], v[174:177], v[98:101]
	v_mfma_f32_16x16x32_bf16 v[86:89], v[198:201], v[182:185], v[86:89]
	v_mfma_f32_16x16x32_bf16 v[82:85], v[212:215], v[182:185], v[82:85]
	v_mfma_f32_16x16x32_bf16 v[70:73], v[198:201], v[190:193], v[70:73]
	v_mfma_f32_16x16x32_bf16 v[66:69], v[212:215], v[190:193], v[66:69]
	v_mfma_f32_16x16x32_bf16 v[118:121], v[202:205], v[170:173], v[118:121]
	v_mfma_f32_16x16x32_bf16 v[114:117], v[216:219], v[170:173], v[114:117]
	v_mfma_f32_16x16x32_bf16 v[102:105], v[202:205], v[178:181], v[102:105]
	v_mfma_f32_16x16x32_bf16 v[98:101], v[216:219], v[178:181], v[98:101]
	v_mfma_f32_16x16x32_bf16 v[86:89], v[202:205], v[186:189], v[86:89]
	v_mfma_f32_16x16x32_bf16 v[82:85], v[216:219], v[186:189], v[82:85]
	v_mfma_f32_16x16x32_bf16 v[70:73], v[202:205], v[194:197], v[70:73]
	v_mfma_f32_16x16x32_bf16 v[66:69], v[216:219], v[194:197], v[66:69]
	s_setprio 0
	s_add_u32 s52, s45, s48
	v_readfirstlane_b32 s10, v141
	s_addc_u32 s53, s51, s49
	v_mov_b32_e32 v149, v130
	v_mov_b32_e32 v208, v1
	s_mov_b32 m0, s10
	v_readfirstlane_b32 s10, v142
	s_barrier
	ds_read_b128 v[166:169], v148 offset:49152
	ds_read_b128 v[170:173], v148 offset:50176
	ds_read_b128 v[174:177], v148 offset:51200
	ds_read_b128 v[178:181], v148 offset:52224
	ds_read_b128 v[182:185], v148 offset:53248
	ds_read_b128 v[186:189], v148 offset:54272
	ds_read_b128 v[190:193], v148 offset:55296
	ds_read_b128 v[194:197], v148 offset:56320
	s_nop 0
	global_load_lds_dwordx4 v208, s[52:53]
	s_mov_b32 m0, s10
	s_nop 0
	global_load_lds_dwordx4 v149, s[52:53]
	s_barrier
	s_waitcnt lgkmcnt(0)
	s_setprio 1
	s_waitcnt lgkmcnt(0)
	v_mfma_f32_16x16x32_bf16 v[62:65], v[150:153], v[166:169], v[62:65]
	v_mfma_f32_16x16x32_bf16 v[58:61], v[158:161], v[166:169], v[58:61]
	v_mfma_f32_16x16x32_bf16 v[46:49], v[150:153], v[174:177], v[46:49]
	v_mfma_f32_16x16x32_bf16 v[42:45], v[158:161], v[174:177], v[42:45]
	v_mfma_f32_16x16x32_bf16 v[30:33], v[150:153], v[182:185], v[30:33]
	v_mfma_f32_16x16x32_bf16 v[26:29], v[158:161], v[182:185], v[26:29]
	v_mfma_f32_16x16x32_bf16 v[14:17], v[150:153], v[190:193], v[14:17]
	v_mfma_f32_16x16x32_bf16 v[10:13], v[158:161], v[190:193], v[10:13]
	v_mfma_f32_16x16x32_bf16 v[62:65], v[154:157], v[170:173], v[62:65]
	v_mfma_f32_16x16x32_bf16 v[58:61], v[162:165], v[170:173], v[58:61]
	v_mfma_f32_16x16x32_bf16 v[46:49], v[154:157], v[178:181], v[46:49]
	v_mfma_f32_16x16x32_bf16 v[42:45], v[162:165], v[178:181], v[42:45]
	v_mfma_f32_16x16x32_bf16 v[30:33], v[154:157], v[186:189], v[30:33]
	v_mfma_f32_16x16x32_bf16 v[26:29], v[162:165], v[186:189], v[26:29]
	v_mfma_f32_16x16x32_bf16 v[14:17], v[154:157], v[194:197], v[14:17]
	v_mfma_f32_16x16x32_bf16 v[10:13], v[162:165], v[194:197], v[10:13]
	s_setprio 0
	s_barrier
	s_add_u32 s48, s58, s48
	v_readfirstlane_b32 s10, v143
	s_addc_u32 s49, s59, s49
	v_mov_b32_e32 v149, v130
	v_mov_b32_e32 v150, v1
	s_mov_b32 m0, s10
	v_readfirstlane_b32 s10, v144
	s_nop 0
	global_load_lds_dwordx4 v150, s[48:49]
	s_mov_b32 m0, s10
	s_nop 0
	global_load_lds_dwordx4 v149, s[48:49]
	s_waitcnt vmcnt(6)
	s_barrier
; #define GM_WAIT_V(n) asm volatile("s_waitcnt vmcnt(" #n ")" ::: "memory")
; #define GM_WAIT_L(n) asm volatile("s_waitcnt lgkmcnt(" #n ")" ::: "memory")
; #define GM_BAR __builtin_amdgcn_s_barrier()
; #define GM_SCHED __builtin_amdgcn_sched_barrier(0)
; #define GM_MMA(ai, bj, At, Bv) do { __builtin_amdgcn_s_setprio(1); \
;         _Pragma("unroll") for (int m = 0; m < 4; ++m) _Pragma("unroll") for (int n = 0; n < 2; ++n) _Pragma("unroll") for (int k = 0; k < 2; ++k) \
;             acc[ai][bj][m][n] = __builtin_amdgcn_mfma_f32_16x16x32_bf16(Bv[n][k], At[m][k], acc[ai][bj][m][n], 0, 0, 0); \
;         __builtin_amdgcn_s_setprio(0); } while (0)
; template <class Epi>
; __device__ __forceinline__ void gemm_phase(const bf16_t* __restrict__ A, const bf16_t* __restrict__ Bt, int M, int N, LAS unsigned char* lds, const Epi& epi, int vcu) {
;     ...
;             GM_BAR; GM_WAIT_L(0); GM_MMA(1, 0, At, B0); GM_BAR; GM_SCHED;
;             GM_STAGE(GM_SB(1, 1), Bt, pcol + HALF, k3);
;             GM_WAIT_V(6); GM_BAR; GM_MMA(1, 1, At, B1); GM_BAR;
;         }
	s_setprio 1
	v_mfma_f32_16x16x32_bf16 v[54:57], v[198:201], v[166:169], v[54:57]
	v_mfma_f32_16x16x32_bf16 v[50:53], v[212:215], v[166:169], v[50:53]
	v_mfma_f32_16x16x32_bf16 v[38:41], v[198:201], v[174:177], v[38:41]
	v_mfma_f32_16x16x32_bf16 v[34:37], v[212:215], v[174:177], v[34:37]
	v_mfma_f32_16x16x32_bf16 v[22:25], v[198:201], v[182:185], v[22:25]
	v_mfma_f32_16x16x32_bf16 v[18:21], v[212:215], v[182:185], v[18:21]
	v_mfma_f32_16x16x32_bf16 v[6:9], v[198:201], v[190:193], v[6:9]
	v_mfma_f32_16x16x32_bf16 v[2:5], v[212:215], v[190:193], v[2:5]
	v_mfma_f32_16x16x32_bf16 v[54:57], v[202:205], v[170:173], v[54:57]
	v_mfma_f32_16x16x32_bf16 v[50:53], v[216:219], v[170:173], v[50:53]
	v_mfma_f32_16x16x32_bf16 v[38:41], v[202:205], v[178:181], v[38:41]
	v_mfma_f32_16x16x32_bf16 v[34:37], v[216:219], v[178:181], v[34:37]
	v_mfma_f32_16x16x32_bf16 v[22:25], v[202:205], v[186:189], v[22:25]
	v_mfma_f32_16x16x32_bf16 v[18:21], v[216:219], v[186:189], v[18:21]
	v_mfma_f32_16x16x32_bf16 v[6:9], v[202:205], v[194:197], v[6:9]
	v_mfma_f32_16x16x32_bf16 v[2:5], v[216:219], v[194:197], v[2:5]
	s_setprio 0
	s_addk_i32 s43, 0x80
	s_add_u32 s46, s46, 0x100
	s_addc_u32 s47, s47, 0
	s_barrier
	s_cbranch_vccz .LBB0_339
	s_add_i32 s10, s42, s4
	v_add_u32_e32 v149, s10, v145
	s_or_b32 s11, s44, s5
	v_lshl_add_u32 v212, v146, 3, s11
	s_lshr_b32 s2, s42, 13
	s_mul_i32 s2, s2, 0x3000
	s_add_u32 s10, s26, s2
	s_addc_u32 s11, s27, 0
	v_lshlrev_b32_e32 v213, 2, v212
	global_load_dwordx4 v[150:153], v213, s[10:11]
	global_load_dwordx4 v[154:157], v213, s[10:11] offset:16
	global_load_dwordx4 v[158:161], v213, s[10:11] offset:512
	global_load_dwordx4 v[162:165], v213, s[10:11] offset:528
	v_lshl_add_u32 v149, v149, 10, v212
	v_lshlrev_b32_e32 v149, 2, v149
	s_mov_b64 s[46:47], s[14:15]
	s_mov_b64 s[10:11], s[62:63]
	global_load_dwordx4 v[166:169], v149, s[46:47]
	global_load_dwordx4 v[170:173], v149, s[46:47] offset:16
	global_load_dwordx4 v[174:177], v149, s[46:47] offset:512
	global_load_dwordx4 v[178:181], v149, s[46:47] offset:528
	s_add_u32 s46, s46, 0x10000
	s_addc_u32 s47, s47, 0
	global_load_dwordx4 v[182:185], v149, s[46:47]
	global_load_dwordx4 v[186:189], v149, s[46:47] offset:16
	global_load_dwordx4 v[190:193], v149, s[46:47] offset:512
	global_load_dwordx4 v[194:197], v149, s[46:47] offset:528
	s_add_u32 s46, s46, 0x10000
	s_addc_u32 s47, s47, 0
	global_load_dwordx4 v[198:201], v149, s[46:47]
	global_load_dwordx4 v[202:205], v149, s[46:47] offset:16
	global_load_dwordx4 v[212:215], v149, s[46:47] offset:512
	global_load_dwordx4 v[216:219], v149, s[46:47] offset:528
	s_add_u32 s46, s46, 0x10000
	s_addc_u32 s47, s47, 0
	s_waitcnt vmcnt(10)
	v_pk_fma_f32 v[126:127], v[126:127], v[150:151], v[166:167]
	v_pk_fma_f32 v[128:129], v[128:129], v[152:153], v[168:169]
	v_pk_fma_f32 v[122:123], v[122:123], v[154:155], v[170:171]
	v_pk_fma_f32 v[124:125], v[124:125], v[156:157], v[172:173]
	global_store_dwordx4 v149, v[126:129], s[10:11]
	global_store_dwordx4 v149, v[122:125], s[10:11] offset:16
	global_load_dwordx4 v[166:169], v149, s[46:47]
	global_load_dwordx4 v[170:173], v149, s[46:47] offset:16
	s_waitcnt vmcnt(12)
	v_pk_fma_f32 v[118:119], v[118:119], v[158:159], v[174:175]
	v_pk_fma_f32 v[120:121], v[120:121], v[160:161], v[176:177]
	v_pk_fma_f32 v[114:115], v[114:115], v[162:163], v[178:179]
	v_pk_fma_f32 v[116:117], v[116:117], v[164:165], v[180:181]
	global_store_dwordx4 v149, v[118:121], s[10:11] offset:512
	global_store_dwordx4 v149, v[114:117], s[10:11] offset:528
	s_add_u32 s10, s10, 0x10000
	s_addc_u32 s11, s11, 0
	global_load_dwordx4 v[174:177], v149, s[46:47] offset:512
	global_load_dwordx4 v[178:181], v149, s[46:47] offset:528
	s_add_u32 s46, s46, 0x50000
	s_addc_u32 s47, s47, 0
	s_waitcnt vmcnt(14)
	v_pk_fma_f32 v[110:111], v[110:111], v[150:151], v[182:183]
	v_pk_fma_f32 v[112:113], v[112:113], v[152:153], v[184:185]
	v_pk_fma_f32 v[106:107], v[106:107], v[154:155], v[186:187]
	v_pk_fma_f32 v[108:109], v[108:109], v[156:157], v[188:189]
	global_store_dwordx4 v149, v[110:113], s[10:11]
	global_store_dwordx4 v149, v[106:109], s[10:11] offset:16
	global_load_dwordx4 v[182:185], v149, s[46:47]
	global_load_dwordx4 v[186:189], v149, s[46:47] offset:16
	s_waitcnt vmcnt(16)
	v_pk_fma_f32 v[102:103], v[102:103], v[158:159], v[190:191]
	v_pk_fma_f32 v[104:105], v[104:105], v[160:161], v[192:193]
	v_pk_fma_f32 v[98:99], v[98:99], v[162:163], v[194:195]
	v_pk_fma_f32 v[100:101], v[100:101], v[164:165], v[196:197]
	global_store_dwordx4 v149, v[102:105], s[10:11] offset:512
	global_store_dwordx4 v149, v[98:101], s[10:11] offset:528
	s_add_u32 s10, s10, 0x10000
	s_addc_u32 s11, s11, 0
	global_load_dwordx4 v[190:193], v149, s[46:47] offset:512
	global_load_dwordx4 v[194:197], v149, s[46:47] offset:528
	s_add_u32 s46, s46, 0x10000
	s_addc_u32 s47, s47, 0
	s_waitcnt vmcnt(18)
	v_pk_fma_f32 v[94:95], v[94:95], v[150:151], v[198:199]
	v_pk_fma_f32 v[96:97], v[96:97], v[152:153], v[200:201]
	v_pk_fma_f32 v[90:91], v[90:91], v[154:155], v[202:203]
	v_pk_fma_f32 v[92:93], v[92:93], v[156:157], v[204:205]
	global_store_dwordx4 v149, v[94:97], s[10:11]
	global_store_dwordx4 v149, v[90:93], s[10:11] offset:16
	global_load_dwordx4 v[198:201], v149, s[46:47]
	global_load_dwordx4 v[202:205], v149, s[46:47] offset:16
	s_waitcnt vmcnt(20)
; #define GM_WAIT_V(n) asm volatile("s_waitcnt vmcnt(" #n ")" ::: "memory")
; #define GM_BAR __builtin_amdgcn_s_barrier()
; #define GM_SCHED __builtin_amdgcn_sched_barrier(0)
; template <class Epi>
; __device__ __forceinline__ void gemm_phase(const bf16_t* __restrict__ A, const bf16_t* __restrict__ Bt, int M, int N, LAS unsigned char* lds, const Epi& epi, int vcu) {
;     ...
;                     for (int bj = 0; bj < 2; ++bj) { const int m = mp * 2 + mq;
;                         epi(brow + ai * HALF + wr * 64 + m * 16 + fre, (bcol + bj * HALF + wc * 32) >> 5, fqe, acc[ai][bj][m][0], acc[ai][bj][m][1]); }
;                 GM_SCHED;
;             }
;         }
;         if (!have_next) break;
;         brow = nrow; bcol = ncol;
;     }
;     GM_WAIT_V(0);
;     if (wr == 0) GM_BAR;
	v_pk_fma_f32 v[86:87], v[86:87], v[158:159], v[212:213]
	v_pk_fma_f32 v[88:89], v[88:89], v[160:161], v[214:215]
	v_pk_fma_f32 v[82:83], v[82:83], v[162:163], v[216:217]
	v_pk_fma_f32 v[84:85], v[84:85], v[164:165], v[218:219]
	global_store_dwordx4 v149, v[86:89], s[10:11] offset:512
	global_store_dwordx4 v149, v[82:85], s[10:11] offset:528
	s_add_u32 s10, s10, 0x10000
	s_addc_u32 s11, s11, 0
	global_load_dwordx4 v[212:215], v149, s[46:47] offset:512
	global_load_dwordx4 v[216:219], v149, s[46:47] offset:528
	s_add_u32 s46, s46, 0x10000
	s_addc_u32 s47, s47, 0
	s_waitcnt vmcnt(20)
	v_pk_fma_f32 v[78:79], v[78:79], v[150:151], v[166:167]
	v_pk_fma_f32 v[80:81], v[80:81], v[152:153], v[168:169]
	v_pk_fma_f32 v[74:75], v[74:75], v[154:155], v[170:171]
	v_pk_fma_f32 v[76:77], v[76:77], v[156:157], v[172:173]
	global_store_dwordx4 v149, v[78:81], s[10:11]
	global_store_dwordx4 v149, v[74:77], s[10:11] offset:16
	global_load_dwordx4 v[166:169], v149, s[46:47]
	global_load_dwordx4 v[170:173], v149, s[46:47] offset:16
	s_waitcnt vmcnt(20)
	v_pk_fma_f32 v[70:71], v[70:71], v[158:159], v[174:175]
	v_pk_fma_f32 v[72:73], v[72:73], v[160:161], v[176:177]
	v_pk_fma_f32 v[66:67], v[66:67], v[162:163], v[178:179]
	v_pk_fma_f32 v[68:69], v[68:69], v[164:165], v[180:181]
	global_store_dwordx4 v149, v[70:73], s[10:11] offset:512
	global_store_dwordx4 v149, v[66:69], s[10:11] offset:528
	s_add_u32 s10, s10, 0x50000
	s_addc_u32 s11, s11, 0
	global_load_dwordx4 v[174:177], v149, s[46:47] offset:512
	global_load_dwordx4 v[178:181], v149, s[46:47] offset:528
	s_add_u32 s46, s46, 0x10000
	s_addc_u32 s47, s47, 0
	s_waitcnt vmcnt(20)
	v_pk_fma_f32 v[62:63], v[62:63], v[150:151], v[182:183]
	v_pk_fma_f32 v[64:65], v[64:65], v[152:153], v[184:185]
	v_pk_fma_f32 v[58:59], v[58:59], v[154:155], v[186:187]
	v_pk_fma_f32 v[60:61], v[60:61], v[156:157], v[188:189]
	global_store_dwordx4 v149, v[62:65], s[10:11]
	global_store_dwordx4 v149, v[58:61], s[10:11] offset:16
	global_load_dwordx4 v[182:185], v149, s[46:47]
	global_load_dwordx4 v[186:189], v149, s[46:47] offset:16
	s_waitcnt vmcnt(20)
	v_pk_fma_f32 v[54:55], v[54:55], v[158:159], v[190:191]
	v_pk_fma_f32 v[56:57], v[56:57], v[160:161], v[192:193]
	v_pk_fma_f32 v[50:51], v[50:51], v[162:163], v[194:195]
	v_pk_fma_f32 v[52:53], v[52:53], v[164:165], v[196:197]
	global_store_dwordx4 v149, v[54:57], s[10:11] offset:512
	global_store_dwordx4 v149, v[50:53], s[10:11] offset:528
	s_add_u32 s10, s10, 0x10000
	s_addc_u32 s11, s11, 0
	global_load_dwordx4 v[190:193], v149, s[46:47] offset:512
	global_load_dwordx4 v[194:197], v149, s[46:47] offset:528
	s_waitcnt vmcnt(20)
	v_pk_fma_f32 v[46:47], v[46:47], v[150:151], v[198:199]
	v_pk_fma_f32 v[48:49], v[48:49], v[152:153], v[200:201]
	v_pk_fma_f32 v[42:43], v[42:43], v[154:155], v[202:203]
	v_pk_fma_f32 v[44:45], v[44:45], v[156:157], v[204:205]
	global_store_dwordx4 v149, v[46:49], s[10:11]
	global_store_dwordx4 v149, v[42:45], s[10:11] offset:16
	s_waitcnt vmcnt(18)
	v_pk_fma_f32 v[38:39], v[38:39], v[158:159], v[212:213]
	v_pk_fma_f32 v[40:41], v[40:41], v[160:161], v[214:215]
	v_pk_fma_f32 v[34:35], v[34:35], v[162:163], v[216:217]
	v_pk_fma_f32 v[36:37], v[36:37], v[164:165], v[218:219]
	global_store_dwordx4 v149, v[38:41], s[10:11] offset:512
	global_store_dwordx4 v149, v[34:37], s[10:11] offset:528
	s_add_u32 s10, s10, 0x10000
	s_addc_u32 s11, s11, 0
	s_waitcnt vmcnt(16)
	v_pk_fma_f32 v[30:31], v[30:31], v[150:151], v[166:167]
	v_pk_fma_f32 v[32:33], v[32:33], v[152:153], v[168:169]
	v_pk_fma_f32 v[26:27], v[26:27], v[154:155], v[170:171]
	v_pk_fma_f32 v[28:29], v[28:29], v[156:157], v[172:173]
	global_store_dwordx4 v149, v[30:33], s[10:11]
	global_store_dwordx4 v149, v[26:29], s[10:11] offset:16
	s_waitcnt vmcnt(14)
	v_pk_fma_f32 v[22:23], v[22:23], v[158:159], v[174:175]
	v_pk_fma_f32 v[24:25], v[24:25], v[160:161], v[176:177]
	v_pk_fma_f32 v[18:19], v[18:19], v[162:163], v[178:179]
	v_pk_fma_f32 v[20:21], v[20:21], v[164:165], v[180:181]
	global_store_dwordx4 v149, v[22:25], s[10:11] offset:512
	global_store_dwordx4 v149, v[18:21], s[10:11] offset:528
	s_add_u32 s10, s10, 0x10000
	s_addc_u32 s11, s11, 0
	s_waitcnt vmcnt(12)
	v_pk_fma_f32 v[14:15], v[14:15], v[150:151], v[182:183]
	v_pk_fma_f32 v[16:17], v[16:17], v[152:153], v[184:185]
	v_pk_fma_f32 v[10:11], v[10:11], v[154:155], v[186:187]
	v_pk_fma_f32 v[12:13], v[12:13], v[156:157], v[188:189]
	global_store_dwordx4 v149, v[14:17], s[10:11]
	global_store_dwordx4 v149, v[10:13], s[10:11] offset:16
	s_waitcnt vmcnt(10)
	v_pk_fma_f32 v[6:7], v[6:7], v[158:159], v[190:191]
	v_pk_fma_f32 v[8:9], v[8:9], v[160:161], v[192:193]
	v_pk_fma_f32 v[2:3], v[2:3], v[162:163], v[194:195]
	v_pk_fma_f32 v[4:5], v[4:5], v[164:165], v[196:197]
	global_store_dwordx4 v149, v[6:9], s[10:11] offset:512
	global_store_dwordx4 v149, v[2:5], s[10:11] offset:528
	v_readlane_b32 s58, v255, 16
	s_and_b64 vcc, exec, s[40:41]
	s_mov_b32 s42, s29
	s_mov_b32 s44, s28
	v_readlane_b32 s59, v255, 17
	v_readlane_b32 s64, v255, 18
	s_mov_b32 s65, 0xf800000
	s_cbranch_vccz .LBB0_332
	s_waitcnt vmcnt(0)
	s_cmpk_gt_u32 s21, 0xff
	s_cbranch_scc1 .LBB0_343
	s_barrier

; #define GM_WAIT_L(n) asm volatile("s_waitcnt lgkmcnt(" #n ")" ::: "memory")
; #define GM_BAR __builtin_amdgcn_s_barrier()
; #define GM_SCHED __builtin_amdgcn_sched_barrier(0)
; #define GM_LDA(dst, b, h) _Pragma("unroll") for (int m = 0; m < 4; ++m) _Pragma("unroll") for (int k = 0; k < 2; ++k) \
;         dst[m][k] = *(const LAS bf16x8*)(GM_SA(b, h) + aoff + (m * 2 + k) * 1024)
; #define GM_LDB(dst, b, h) _Pragma("unroll") for (int n = 0; n < 2; ++n) _Pragma("unroll") for (int k = 0; k < 2; ++k) \
;         dst[n][k] = *(const LAS bf16x8*)(GM_SB(b, h) + boff + (n * 2 + k) * 1024)
; #define GM_MMA(ai, bj, At, Bv) do { __builtin_amdgcn_s_setprio(1); \
;         _Pragma("unroll") for (int m = 0; m < 4; ++m) _Pragma("unroll") for (int n = 0; n < 2; ++n) _Pragma("unroll") for (int k = 0; k < 2; ++k) \
;             acc[ai][bj][m][n] = __builtin_amdgcn_mfma_f32_16x16x32_bf16(Bv[n][k], At[m][k], acc[ai][bj][m][n], 0, 0, 0); \
;         __builtin_amdgcn_s_setprio(0); } while (0)
; template <class Epi>
; __device__ __forceinline__ void gemm_phase(const bf16_t* __restrict__ A, const bf16_t* __restrict__ Bt, int M, int N, LAS unsigned char* lds, const Epi& epi, int vcu) {
;     ...
;         f32x4 acc[2][2][4][2];
; #pragma unroll
;         for (int a = 0; a < 2; ++a)
; #pragma unroll
;             for (int b = 0; b < 2; ++b)
; #pragma unroll
;                 for (int m = 0; m < 4; ++m)
; #pragma unroll
;                     for (int n = 0; n < 2; ++n) acc[a][b][m][n] = (f32x4){0.f, 0.f, 0.f, 0.f};
;         bf16x8 At[4][2], B0[2][2], B1[2][2];
;         for (int t = 0; t < NT; t += 2) {
;             const bool lastk = (t + 2 >= NT);
;             const int prow = lastk ? nrow : brow, pcol = lastk ? ncol : bcol, k2 = lastk ? 0 : t + 2, k3 = lastk ? 1 : t + 3;
;             GM_LDB(B0, 0, 0); GM_SCHED; GM_LDA(At, 0, 0); GM_STAGE(GM_SA(1, 1), A, brow + HALF, t + 1);
;             GM_WAIT_L(8); GM_BAR; GM_WAIT_L(0); GM_MMA(0, 0, At, B0); GM_BAR; GM_SCHED;
.LBB0_375:
	s_add_i32 s15, s15, 2
	v_add_u32_e32 v149, s88, v147
	s_cmp_gt_u32 s15, 13
	ds_read_b128 v[150:153], v149
	ds_read_b128 v[154:157], v149 offset:1024
	ds_read_b128 v[158:161], v149 offset:2048
	ds_read_b128 v[162:165], v149 offset:3072
	s_cselect_b64 s[44:45], -1, 0
	s_and_b64 s[44:45], s[44:45], exec
	s_cselect_b32 s44, 64, s27
	s_sub_i32 s10, s27, 64
	s_cmp_gt_u32 s15, 13
	s_cselect_b64 s[46:47], -1, 0
	s_and_b64 vcc, s[46:47], exec
	s_cselect_b32 s46, s28, s14
	s_cselect_b32 s48, s25, s26
	s_cselect_b32 s96, 0, s10
	v_add_u32_e32 v199, 0xc000, v133
	v_mov_b32_e32 v149, v130
	v_mov_b32_e32 v198, v1
	v_readfirstlane_b32 s10, v199
	ds_read_b128 v[166:169], v148
	ds_read_b128 v[170:173], v148 offset:1024
	ds_read_b128 v[174:177], v148 offset:2048
	ds_read_b128 v[178:181], v148 offset:3072
	ds_read_b128 v[182:185], v148 offset:4096
	ds_read_b128 v[186:189], v148 offset:5120
	ds_read_b128 v[190:193], v148 offset:6144
	ds_read_b128 v[194:197], v148 offset:7168
	s_mov_b32 m0, s10
	s_nop 0
	global_load_lds_dwordx4 v198, s[42:43]
	v_add_u32_e32 v198, 0xe000, v133
	s_nop 0
	v_readfirstlane_b32 s10, v198
	s_mov_b32 m0, s10
	s_nop 0
	global_load_lds_dwordx4 v149, s[42:43]
	s_cmp_lg_u32 s15, 0
	s_cbranch_scc1 .Lclr_skip2
	v_mov_b32_e32 v3, v2
	v_mov_b64_e32 v[4:5], 0
	v_mov_b64_e32 v[6:7], 0
	v_mov_b64_e32 v[8:9], 0
	v_mov_b64_e32 v[18:19], 0
	v_mov_b64_e32 v[20:21], 0
	v_mov_b64_e32 v[22:23], 0
	v_mov_b64_e32 v[24:25], 0
	v_mov_b64_e32 v[34:35], 0
	v_mov_b64_e32 v[36:37], 0
	v_mov_b64_e32 v[38:39], 0
	v_mov_b64_e32 v[40:41], 0
	v_mov_b64_e32 v[50:51], 0
	v_mov_b64_e32 v[52:53], 0
	v_mov_b64_e32 v[54:55], 0
	v_mov_b64_e32 v[56:57], 0
	v_mov_b64_e32 v[10:11], 0
	v_mov_b64_e32 v[12:13], 0
	v_mov_b64_e32 v[14:15], 0
	v_mov_b64_e32 v[16:17], 0
	v_mov_b64_e32 v[26:27], 0
	v_mov_b64_e32 v[28:29], 0
	v_mov_b64_e32 v[30:31], 0
	v_mov_b64_e32 v[32:33], 0
	v_mov_b64_e32 v[42:43], 0
	v_mov_b64_e32 v[44:45], 0
	v_mov_b64_e32 v[46:47], 0
	v_mov_b64_e32 v[48:49], 0
	v_mov_b64_e32 v[58:59], 0
	v_mov_b64_e32 v[60:61], 0
	v_mov_b64_e32 v[62:63], 0
	v_mov_b64_e32 v[64:65], 0
	v_mov_b64_e32 v[66:67], 0
	v_mov_b64_e32 v[68:69], 0
	v_mov_b64_e32 v[70:71], 0
	v_mov_b64_e32 v[72:73], 0
	v_mov_b64_e32 v[82:83], 0
	v_mov_b64_e32 v[84:85], 0
	v_mov_b64_e32 v[86:87], 0
	v_mov_b64_e32 v[88:89], 0
	v_mov_b64_e32 v[98:99], 0
	v_mov_b64_e32 v[100:101], 0
	v_mov_b64_e32 v[102:103], 0
	v_mov_b64_e32 v[104:105], 0
	v_mov_b64_e32 v[114:115], 0
	v_mov_b64_e32 v[116:117], 0
	v_mov_b64_e32 v[118:119], 0
	v_mov_b64_e32 v[120:121], 0
	v_mov_b64_e32 v[74:75], 0
	v_mov_b64_e32 v[76:77], 0
	v_mov_b64_e32 v[78:79], 0
	v_mov_b64_e32 v[80:81], 0
	v_mov_b64_e32 v[90:91], 0
	v_mov_b64_e32 v[92:93], 0
	v_mov_b64_e32 v[94:95], 0
	v_mov_b64_e32 v[96:97], 0
	v_mov_b64_e32 v[106:107], 0
	v_mov_b64_e32 v[108:109], 0
	v_mov_b64_e32 v[110:111], 0
	v_mov_b64_e32 v[112:113], 0
	v_mov_b64_e32 v[122:123], 0
	v_mov_b64_e32 v[124:125], 0
	v_mov_b64_e32 v[126:127], 0
	v_mov_b64_e32 v[128:129], 0
.Lclr_skip2:
	s_waitcnt lgkmcnt(8)
	s_barrier
	s_waitcnt lgkmcnt(0)
	s_setprio 1
	s_waitcnt lgkmcnt(0)
	v_mfma_f32_16x16x32_bf16 v[126:129], v[150:153], v[166:169], v[126:129]
	v_mfma_f32_16x16x32_bf16 v[122:125], v[158:161], v[166:169], v[122:125]
	v_mfma_f32_16x16x32_bf16 v[110:113], v[150:153], v[174:177], v[110:113]
	v_mfma_f32_16x16x32_bf16 v[106:109], v[158:161], v[174:177], v[106:109]
	v_mfma_f32_16x16x32_bf16 v[94:97], v[150:153], v[182:185], v[94:97]
	v_mfma_f32_16x16x32_bf16 v[90:93], v[158:161], v[182:185], v[90:93]
	v_mfma_f32_16x16x32_bf16 v[78:81], v[150:153], v[190:193], v[78:81]
	v_mfma_f32_16x16x32_bf16 v[74:77], v[158:161], v[190:193], v[74:77]
	v_mfma_f32_16x16x32_bf16 v[126:129], v[154:157], v[170:173], v[126:129]
	v_mfma_f32_16x16x32_bf16 v[122:125], v[162:165], v[170:173], v[122:125]
	v_mfma_f32_16x16x32_bf16 v[110:113], v[154:157], v[178:181], v[110:113]
	v_mfma_f32_16x16x32_bf16 v[106:109], v[162:165], v[178:181], v[106:109]
	v_mfma_f32_16x16x32_bf16 v[94:97], v[154:157], v[186:189], v[94:97]
	v_mfma_f32_16x16x32_bf16 v[90:93], v[162:165], v[186:189], v[90:93]
	v_mfma_f32_16x16x32_bf16 v[78:81], v[154:157], v[194:197], v[78:81]
	v_mfma_f32_16x16x32_bf16 v[74:77], v[162:165], v[194:197], v[74:77]
	s_setprio 0
	s_barrier
	s_ashr_i32 s49, s48, 31
	s_lshl_b64 s[48:49], s[48:49], 11
	s_add_u32 s10, s9, s48
	s_addc_u32 s11, s33, s49
	s_lshl_b64 s[48:49], s[96:97], 1
	v_add_u32_e32 v149, s89, v147
	s_add_u32 s52, s10, s48
	v_readfirstlane_b32 s29, v131
	ds_read_b128 v[198:201], v149
	ds_read_b128 v[202:205], v149 offset:1024
	ds_read_b128 v[212:215], v149 offset:2048
	ds_read_b128 v[216:219], v149 offset:3072
	s_addc_u32 s53, s11, s49
	v_mov_b32_e32 v149, v130
	v_mov_b32_e32 v208, v1
	s_mov_b32 m0, s29
	v_readfirstlane_b32 s29, v132
	s_nop 0
	global_load_lds_dwordx4 v208, s[52:53]
	s_mov_b32 m0, s29
	s_nop 0
	global_load_lds_dwordx4 v149, s[52:53]
	s_barrier
; #define GM_WAIT_V(n) asm volatile("s_waitcnt vmcnt(" #n ")" ::: "memory")
; #define GM_WAIT_L(n) asm volatile("s_waitcnt lgkmcnt(" #n ")" ::: "memory")
; #define GM_BAR __builtin_amdgcn_s_barrier()
; #define GM_SCHED __builtin_amdgcn_sched_barrier(0)
; #define GM_LDA(dst, b, h) _Pragma("unroll") for (int m = 0; m < 4; ++m) _Pragma("unroll") for (int k = 0; k < 2; ++k) \
;         dst[m][k] = *(const LAS bf16x8*)(GM_SA(b, h) + aoff + (m * 2 + k) * 1024)
; #define GM_LDB(dst, b, h) _Pragma("unroll") for (int n = 0; n < 2; ++n) _Pragma("unroll") for (int k = 0; k < 2; ++k) \
;         dst[n][k] = *(const LAS bf16x8*)(GM_SB(b, h) + boff + (n * 2 + k) * 1024)
; #define GM_MMA(ai, bj, At, Bv) do { __builtin_amdgcn_s_setprio(1); \
;         _Pragma("unroll") for (int m = 0; m < 4; ++m) _Pragma("unroll") for (int n = 0; n < 2; ++n) _Pragma("unroll") for (int k = 0; k < 2; ++k) \
;             acc[ai][bj][m][n] = __builtin_amdgcn_mfma_f32_16x16x32_bf16(Bv[n][k], At[m][k], acc[ai][bj][m][n], 0, 0, 0); \
;         __builtin_amdgcn_s_setprio(0); } while (0)
; template <class Epi>
; __device__ __forceinline__ void gemm_phase(const bf16_t* __restrict__ A, const bf16_t* __restrict__ Bt, int M, int N, LAS unsigned char* lds, const Epi& epi, int vcu) {
;     ...
;             GM_LDB(B1, 0, 1); GM_STAGE(GM_SB(0, 0), Bt, pcol, k2);
;             GM_BAR; GM_WAIT_L(0); GM_MMA(0, 1, At, B1); GM_BAR;
;             GM_LDA(At, 0, 1); GM_STAGE(GM_SA(0, 0), A, prow, k2);
;             GM_BAR; GM_WAIT_L(0); GM_MMA(1, 0, At, B0); GM_BAR; GM_SCHED;
;             GM_STAGE(GM_SB(0, 1), Bt, pcol + HALF, k2);
;             GM_WAIT_V(6); GM_BAR; GM_MMA(1, 1, At, B1); GM_BAR;
;             GM_LDB(B0, 1, 0); GM_SCHED; GM_LDA(At, 1, 0); GM_STAGE(GM_SA(0, 1), A, prow + HALF, k2);
;             GM_WAIT_L(8); GM_BAR; GM_WAIT_L(0); GM_MMA(0, 0, At, B0); GM_BAR; GM_SCHED;
	s_waitcnt lgkmcnt(0)
	s_setprio 1
	s_waitcnt lgkmcnt(0)
	v_mfma_f32_16x16x32_bf16 v[118:121], v[198:201], v[166:169], v[118:121]
	v_mfma_f32_16x16x32_bf16 v[114:117], v[212:215], v[166:169], v[114:117]
	v_mfma_f32_16x16x32_bf16 v[102:105], v[198:201], v[174:177], v[102:105]
	v_mfma_f32_16x16x32_bf16 v[98:101], v[212:215], v[174:177], v[98:101]
	v_mfma_f32_16x16x32_bf16 v[86:89], v[198:201], v[182:185], v[86:89]
	v_mfma_f32_16x16x32_bf16 v[82:85], v[212:215], v[182:185], v[82:85]
	v_mfma_f32_16x16x32_bf16 v[70:73], v[198:201], v[190:193], v[70:73]
	v_mfma_f32_16x16x32_bf16 v[66:69], v[212:215], v[190:193], v[66:69]
	v_mfma_f32_16x16x32_bf16 v[118:121], v[202:205], v[170:173], v[118:121]
	v_mfma_f32_16x16x32_bf16 v[114:117], v[216:219], v[170:173], v[114:117]
	v_mfma_f32_16x16x32_bf16 v[102:105], v[202:205], v[178:181], v[102:105]
	v_mfma_f32_16x16x32_bf16 v[98:101], v[216:219], v[178:181], v[98:101]
	v_mfma_f32_16x16x32_bf16 v[86:89], v[202:205], v[186:189], v[86:89]
	v_mfma_f32_16x16x32_bf16 v[82:85], v[216:219], v[186:189], v[82:85]
	v_mfma_f32_16x16x32_bf16 v[70:73], v[202:205], v[194:197], v[70:73]
	v_mfma_f32_16x16x32_bf16 v[66:69], v[216:219], v[194:197], v[66:69]
	s_setprio 0
	s_ashr_i32 s47, s46, 31
	s_lshl_b64 s[46:47], s[46:47], 11
	s_add_u32 s29, s74, s46
	s_addc_u32 s34, s75, s47
	s_add_u32 s46, s29, s48
	v_readfirstlane_b32 s37, v133
	s_addc_u32 s47, s34, s49
	v_mov_b32_e32 v149, v130
	v_mov_b32_e32 v208, v1
	s_mov_b32 m0, s37
	v_readfirstlane_b32 s37, v134
	s_barrier
	ds_read_b128 v[166:169], v148 offset:16384
	ds_read_b128 v[170:173], v148 offset:17408
	ds_read_b128 v[174:177], v148 offset:18432
	ds_read_b128 v[178:181], v148 offset:19456
	ds_read_b128 v[182:185], v148 offset:20480
	ds_read_b128 v[186:189], v148 offset:21504
	ds_read_b128 v[190:193], v148 offset:22528
	ds_read_b128 v[194:197], v148 offset:23552
	s_nop 0
	global_load_lds_dwordx4 v208, s[46:47]
	s_mov_b32 m0, s37
	s_nop 0
	global_load_lds_dwordx4 v149, s[46:47]
	s_barrier
	s_waitcnt lgkmcnt(0)
	s_setprio 1
	s_waitcnt lgkmcnt(0)
	v_mfma_f32_16x16x32_bf16 v[62:65], v[150:153], v[166:169], v[62:65]
	v_mfma_f32_16x16x32_bf16 v[58:61], v[158:161], v[166:169], v[58:61]
	v_mfma_f32_16x16x32_bf16 v[46:49], v[150:153], v[174:177], v[46:49]
	v_mfma_f32_16x16x32_bf16 v[42:45], v[158:161], v[174:177], v[42:45]
	v_mfma_f32_16x16x32_bf16 v[30:33], v[150:153], v[182:185], v[30:33]
	v_mfma_f32_16x16x32_bf16 v[26:29], v[158:161], v[182:185], v[26:29]
	v_mfma_f32_16x16x32_bf16 v[14:17], v[150:153], v[190:193], v[14:17]
	v_mfma_f32_16x16x32_bf16 v[10:13], v[158:161], v[190:193], v[10:13]
	v_mfma_f32_16x16x32_bf16 v[62:65], v[154:157], v[170:173], v[62:65]
	v_mfma_f32_16x16x32_bf16 v[58:61], v[162:165], v[170:173], v[58:61]
	v_mfma_f32_16x16x32_bf16 v[46:49], v[154:157], v[178:181], v[46:49]
	v_mfma_f32_16x16x32_bf16 v[42:45], v[162:165], v[178:181], v[42:45]
	v_mfma_f32_16x16x32_bf16 v[30:33], v[154:157], v[186:189], v[30:33]
	v_mfma_f32_16x16x32_bf16 v[26:29], v[162:165], v[186:189], v[26:29]
	v_mfma_f32_16x16x32_bf16 v[14:17], v[154:157], v[194:197], v[14:17]
	v_mfma_f32_16x16x32_bf16 v[10:13], v[162:165], v[194:197], v[10:13]
	s_setprio 0
	s_barrier
	s_add_u32 s37, s10, 0x40000
	s_addc_u32 s51, s11, 0
	s_add_u32 s48, s37, s48
	v_readfirstlane_b32 s45, v135
	s_addc_u32 s49, s51, s49
	v_mov_b32_e32 v149, v130
	v_mov_b32_e32 v150, v1
	s_mov_b32 m0, s45
	v_readfirstlane_b32 s45, v136
	s_nop 0
	global_load_lds_dwordx4 v150, s[48:49]
	s_mov_b32 m0, s45
	s_nop 0
	global_load_lds_dwordx4 v149, s[48:49]
	s_waitcnt vmcnt(6)
	s_barrier
	s_setprio 1
	v_mfma_f32_16x16x32_bf16 v[54:57], v[198:201], v[166:169], v[54:57]
	v_mfma_f32_16x16x32_bf16 v[50:53], v[212:215], v[166:169], v[50:53]
	v_mfma_f32_16x16x32_bf16 v[38:41], v[198:201], v[174:177], v[38:41]
	v_mfma_f32_16x16x32_bf16 v[34:37], v[212:215], v[174:177], v[34:37]
	v_mfma_f32_16x16x32_bf16 v[22:25], v[198:201], v[182:185], v[22:25]
	v_mfma_f32_16x16x32_bf16 v[18:21], v[212:215], v[182:185], v[18:21]
	v_mfma_f32_16x16x32_bf16 v[6:9], v[198:201], v[190:193], v[6:9]
	v_mfma_f32_16x16x32_bf16 v[2:5], v[212:215], v[190:193], v[2:5]
	v_mfma_f32_16x16x32_bf16 v[54:57], v[202:205], v[170:173], v[54:57]
	v_mfma_f32_16x16x32_bf16 v[50:53], v[216:219], v[170:173], v[50:53]
	v_mfma_f32_16x16x32_bf16 v[38:41], v[202:205], v[178:181], v[38:41]
	v_mfma_f32_16x16x32_bf16 v[34:37], v[216:219], v[178:181], v[34:37]
	v_mfma_f32_16x16x32_bf16 v[22:25], v[202:205], v[186:189], v[22:25]
	v_mfma_f32_16x16x32_bf16 v[18:21], v[216:219], v[186:189], v[18:21]
	v_mfma_f32_16x16x32_bf16 v[6:9], v[202:205], v[194:197], v[6:9]
	v_mfma_f32_16x16x32_bf16 v[2:5], v[216:219], v[194:197], v[2:5]
	s_setprio 0
	v_add_u32_e32 v149, s16, v147
	s_barrier
	ds_read_b128 v[150:153], v149
	ds_read_b128 v[154:157], v149 offset:1024
	ds_read_b128 v[158:161], v149 offset:2048
	ds_read_b128 v[162:165], v149 offset:3072
	s_add_u32 s46, s46, 0x40000
	v_readfirstlane_b32 s45, v137
	s_addc_u32 s47, s47, 0
	v_mov_b32_e32 v149, v130
	v_mov_b32_e32 v198, v1
	s_mov_b32 m0, s45
	v_readfirstlane_b32 s45, v138
	ds_read_b128 v[166:169], v148 offset:32768
	ds_read_b128 v[170:173], v148 offset:33792
	ds_read_b128 v[174:177], v148 offset:34816
	ds_read_b128 v[178:181], v148 offset:35840
	ds_read_b128 v[182:185], v148 offset:36864
	ds_read_b128 v[186:189], v148 offset:37888
	ds_read_b128 v[190:193], v148 offset:38912
	ds_read_b128 v[194:197], v148 offset:39936
	s_nop 0
	global_load_lds_dwordx4 v198, s[46:47]
	s_mov_b32 m0, s45
	s_nop 0
	global_load_lds_dwordx4 v149, s[46:47]
	s_waitcnt lgkmcnt(8)
	s_barrier
; #define GM_WAIT_L(n) asm volatile("s_waitcnt lgkmcnt(" #n ")" ::: "memory")
; #define GM_BAR __builtin_amdgcn_s_barrier()
; #define GM_SCHED __builtin_amdgcn_sched_barrier(0)
; #define GM_LDA(dst, b, h) _Pragma("unroll") for (int m = 0; m < 4; ++m) _Pragma("unroll") for (int k = 0; k < 2; ++k) \
;         dst[m][k] = *(const LAS bf16x8*)(GM_SA(b, h) + aoff + (m * 2 + k) * 1024)
; #define GM_LDB(dst, b, h) _Pragma("unroll") for (int n = 0; n < 2; ++n) _Pragma("unroll") for (int k = 0; k < 2; ++k) \
;         dst[n][k] = *(const LAS bf16x8*)(GM_SB(b, h) + boff + (n * 2 + k) * 1024)
; #define GM_MMA(ai, bj, At, Bv) do { __builtin_amdgcn_s_setprio(1); \
;         _Pragma("unroll") for (int m = 0; m < 4; ++m) _Pragma("unroll") for (int n = 0; n < 2; ++n) _Pragma("unroll") for (int k = 0; k < 2; ++k) \
;             acc[ai][bj][m][n] = __builtin_amdgcn_mfma_f32_16x16x32_bf16(Bv[n][k], At[m][k], acc[ai][bj][m][n], 0, 0, 0); \
;         __builtin_amdgcn_s_setprio(0); } while (0)
; template <class Epi>
; __device__ __forceinline__ void gemm_phase(const bf16_t* __restrict__ A, const bf16_t* __restrict__ Bt, int M, int N, LAS unsigned char* lds, const Epi& epi, int vcu) {
;     ...
;             GM_WAIT_L(8); GM_BAR; GM_WAIT_L(0); GM_MMA(0, 0, At, B0); GM_BAR; GM_SCHED;
;             GM_LDB(B1, 1, 1); GM_STAGE(GM_SB(1, 0), Bt, pcol, k3);
;             GM_BAR; GM_WAIT_L(0); GM_MMA(0, 1, At, B1); GM_BAR;
;             GM_LDA(At, 1, 1); GM_STAGE(GM_SA(1, 0), A, prow, k3);
;             GM_BAR; GM_WAIT_L(0); GM_MMA(1, 0, At, B0); GM_BAR; GM_SCHED;
	s_waitcnt lgkmcnt(0)
	s_setprio 1
	s_waitcnt lgkmcnt(0)
	v_mfma_f32_16x16x32_bf16 v[126:129], v[150:153], v[166:169], v[126:129]
	v_mfma_f32_16x16x32_bf16 v[122:125], v[158:161], v[166:169], v[122:125]
	v_mfma_f32_16x16x32_bf16 v[110:113], v[150:153], v[174:177], v[110:113]
	v_mfma_f32_16x16x32_bf16 v[106:109], v[158:161], v[174:177], v[106:109]
	v_mfma_f32_16x16x32_bf16 v[94:97], v[150:153], v[182:185], v[94:97]
	v_mfma_f32_16x16x32_bf16 v[90:93], v[158:161], v[182:185], v[90:93]
	v_mfma_f32_16x16x32_bf16 v[78:81], v[150:153], v[190:193], v[78:81]
	v_mfma_f32_16x16x32_bf16 v[74:77], v[158:161], v[190:193], v[74:77]
	v_mfma_f32_16x16x32_bf16 v[126:129], v[154:157], v[170:173], v[126:129]
	v_mfma_f32_16x16x32_bf16 v[122:125], v[162:165], v[170:173], v[122:125]
	v_mfma_f32_16x16x32_bf16 v[110:113], v[154:157], v[178:181], v[110:113]
	v_mfma_f32_16x16x32_bf16 v[106:109], v[162:165], v[178:181], v[106:109]
	v_mfma_f32_16x16x32_bf16 v[94:97], v[154:157], v[186:189], v[94:97]
	v_mfma_f32_16x16x32_bf16 v[90:93], v[162:165], v[186:189], v[90:93]
	v_mfma_f32_16x16x32_bf16 v[78:81], v[154:157], v[194:197], v[78:81]
	v_mfma_f32_16x16x32_bf16 v[74:77], v[162:165], v[194:197], v[74:77]
	s_setprio 0
	s_barrier
	s_mov_b32 s45, s97
	s_lshl_b64 s[44:45], s[44:45], 1
	v_add_u32_e32 v149, s17, v147
	s_add_u32 s46, s10, s44
	v_readfirstlane_b32 s10, v139
	ds_read_b128 v[198:201], v149
	ds_read_b128 v[202:205], v149 offset:1024
	ds_read_b128 v[212:215], v149 offset:2048
	ds_read_b128 v[216:219], v149 offset:3072
	s_addc_u32 s47, s11, s45
	v_mov_b32_e32 v149, v130
	v_mov_b32_e32 v208, v1
	s_mov_b32 m0, s10
	v_readfirstlane_b32 s10, v140
	s_nop 0
	global_load_lds_dwordx4 v208, s[46:47]
	s_mov_b32 m0, s10
	s_nop 0
	global_load_lds_dwordx4 v149, s[46:47]
	s_barrier
	s_waitcnt lgkmcnt(0)
	s_setprio 1
	s_waitcnt lgkmcnt(0)
	v_mfma_f32_16x16x32_bf16 v[118:121], v[198:201], v[166:169], v[118:121]
	v_mfma_f32_16x16x32_bf16 v[114:117], v[212:215], v[166:169], v[114:117]
	v_mfma_f32_16x16x32_bf16 v[102:105], v[198:201], v[174:177], v[102:105]
	v_mfma_f32_16x16x32_bf16 v[98:101], v[212:215], v[174:177], v[98:101]
	v_mfma_f32_16x16x32_bf16 v[86:89], v[198:201], v[182:185], v[86:89]
	v_mfma_f32_16x16x32_bf16 v[82:85], v[212:215], v[182:185], v[82:85]
	v_mfma_f32_16x16x32_bf16 v[70:73], v[198:201], v[190:193], v[70:73]
	v_mfma_f32_16x16x32_bf16 v[66:69], v[212:215], v[190:193], v[66:69]
	v_mfma_f32_16x16x32_bf16 v[118:121], v[202:205], v[170:173], v[118:121]
	v_mfma_f32_16x16x32_bf16 v[114:117], v[216:219], v[170:173], v[114:117]
	v_mfma_f32_16x16x32_bf16 v[102:105], v[202:205], v[178:181], v[102:105]
	v_mfma_f32_16x16x32_bf16 v[98:101], v[216:219], v[178:181], v[98:101]
	v_mfma_f32_16x16x32_bf16 v[86:89], v[202:205], v[186:189], v[86:89]
	v_mfma_f32_16x16x32_bf16 v[82:85], v[216:219], v[186:189], v[82:85]
	v_mfma_f32_16x16x32_bf16 v[70:73], v[202:205], v[194:197], v[70:73]
	v_mfma_f32_16x16x32_bf16 v[66:69], v[216:219], v[194:197], v[66:69]
	s_setprio 0
	s_add_u32 s46, s29, s44
	v_readfirstlane_b32 s10, v141
	s_addc_u32 s47, s34, s45
	v_mov_b32_e32 v149, v130
	v_mov_b32_e32 v208, v1
	s_mov_b32 m0, s10
	v_readfirstlane_b32 s10, v142
	s_barrier
	ds_read_b128 v[166:169], v148 offset:49152
	ds_read_b128 v[170:173], v148 offset:50176
	ds_read_b128 v[174:177], v148 offset:51200
	ds_read_b128 v[178:181], v148 offset:52224
	ds_read_b128 v[182:185], v148 offset:53248
	ds_read_b128 v[186:189], v148 offset:54272
	ds_read_b128 v[190:193], v148 offset:55296
	ds_read_b128 v[194:197], v148 offset:56320
	s_nop 0
	global_load_lds_dwordx4 v208, s[46:47]
	s_mov_b32 m0, s10
	s_nop 0
	global_load_lds_dwordx4 v149, s[46:47]
	s_barrier
; __device__ __forceinline__ float silu_f(float v) { return v * __builtin_amdgcn_rcpf(1.0f + __builtin_amdgcn_exp2f(-LOG2E * v)); }
; #define GM_WAIT_V(n) asm volatile("s_waitcnt vmcnt(" #n ")" ::: "memory")
; #define GM_WAIT_L(n) asm volatile("s_waitcnt lgkmcnt(" #n ")" ::: "memory")
; #define GM_BAR __builtin_amdgcn_s_barrier()
; #define GM_SCHED __builtin_amdgcn_sched_barrier(0)
; #define GM_MMA(ai, bj, At, Bv) do { __builtin_amdgcn_s_setprio(1); \
;         _Pragma("unroll") for (int m = 0; m < 4; ++m) _Pragma("unroll") for (int n = 0; n < 2; ++n) _Pragma("unroll") for (int k = 0; k < 2; ++k) \
;             acc[ai][bj][m][n] = __builtin_amdgcn_mfma_f32_16x16x32_bf16(Bv[n][k], At[m][k], acc[ai][bj][m][n], 0, 0, 0); \
;         __builtin_amdgcn_s_setprio(0); } while (0)
; template <class Epi>
; __device__ __forceinline__ void gemm_phase(const bf16_t* __restrict__ A, const bf16_t* __restrict__ Bt, int M, int N, LAS unsigned char* lds, const Epi& epi, int vcu) {
;     ...
;             GM_BAR; GM_WAIT_L(0); GM_MMA(1, 0, At, B0); GM_BAR; GM_SCHED;
;             GM_STAGE(GM_SB(1, 1), Bt, pcol + HALF, k3);
;             GM_WAIT_V(6); GM_BAR; GM_MMA(1, 1, At, B1); GM_BAR;
;     __device__ __forceinline__ void operator()(int row, int G, int fq, f32x4 v0, f32x4 v1) const {
;     ...
;         if (G < 64) r = v0 * v1;
;         else { r[0] = v0[0] * silu_f(v1[0]); r[1] = v0[1] * silu_f(v1[1]); r[2] = v0[2] * silu_f(v1[2]); r[3] = v0[3] * silu_f(v1[3]); }
	s_waitcnt lgkmcnt(0)
	s_setprio 1
	s_waitcnt lgkmcnt(0)
	v_mfma_f32_16x16x32_bf16 v[62:65], v[150:153], v[166:169], v[62:65]
	v_mfma_f32_16x16x32_bf16 v[58:61], v[158:161], v[166:169], v[58:61]
	v_mfma_f32_16x16x32_bf16 v[46:49], v[150:153], v[174:177], v[46:49]
	v_mfma_f32_16x16x32_bf16 v[42:45], v[158:161], v[174:177], v[42:45]
	v_mfma_f32_16x16x32_bf16 v[30:33], v[150:153], v[182:185], v[30:33]
	v_mfma_f32_16x16x32_bf16 v[26:29], v[158:161], v[182:185], v[26:29]
	v_mfma_f32_16x16x32_bf16 v[14:17], v[150:153], v[190:193], v[14:17]
	v_mfma_f32_16x16x32_bf16 v[10:13], v[158:161], v[190:193], v[10:13]
	v_mfma_f32_16x16x32_bf16 v[62:65], v[154:157], v[170:173], v[62:65]
	v_mfma_f32_16x16x32_bf16 v[58:61], v[162:165], v[170:173], v[58:61]
	v_mfma_f32_16x16x32_bf16 v[46:49], v[154:157], v[178:181], v[46:49]
	v_mfma_f32_16x16x32_bf16 v[42:45], v[162:165], v[178:181], v[42:45]
	v_mfma_f32_16x16x32_bf16 v[30:33], v[154:157], v[186:189], v[30:33]
	v_mfma_f32_16x16x32_bf16 v[26:29], v[162:165], v[186:189], v[26:29]
	v_mfma_f32_16x16x32_bf16 v[14:17], v[154:157], v[194:197], v[14:17]
	v_mfma_f32_16x16x32_bf16 v[10:13], v[162:165], v[194:197], v[10:13]
	s_setprio 0
	s_barrier
	s_add_u32 s44, s37, s44
	v_readfirstlane_b32 s10, v143
	s_addc_u32 s45, s51, s45
	v_mov_b32_e32 v149, v130
	v_mov_b32_e32 v150, v1
	s_mov_b32 m0, s10
	v_readfirstlane_b32 s10, v144
	s_nop 0
	global_load_lds_dwordx4 v150, s[44:45]
	s_mov_b32 m0, s10
	s_nop 0
	global_load_lds_dwordx4 v149, s[44:45]
	s_waitcnt vmcnt(6)
	s_barrier
	s_setprio 1
	v_mfma_f32_16x16x32_bf16 v[54:57], v[198:201], v[166:169], v[54:57]
	v_mfma_f32_16x16x32_bf16 v[50:53], v[212:215], v[166:169], v[50:53]
	v_mfma_f32_16x16x32_bf16 v[38:41], v[198:201], v[174:177], v[38:41]
	v_mfma_f32_16x16x32_bf16 v[34:37], v[212:215], v[174:177], v[34:37]
	v_mfma_f32_16x16x32_bf16 v[22:25], v[198:201], v[182:185], v[22:25]
	v_mfma_f32_16x16x32_bf16 v[18:21], v[212:215], v[182:185], v[18:21]
	v_mfma_f32_16x16x32_bf16 v[6:9], v[198:201], v[190:193], v[6:9]
	v_mfma_f32_16x16x32_bf16 v[2:5], v[212:215], v[190:193], v[2:5]
	v_mfma_f32_16x16x32_bf16 v[54:57], v[202:205], v[170:173], v[54:57]
	v_mfma_f32_16x16x32_bf16 v[50:53], v[216:219], v[170:173], v[50:53]
	v_mfma_f32_16x16x32_bf16 v[38:41], v[202:205], v[178:181], v[38:41]
	v_mfma_f32_16x16x32_bf16 v[34:37], v[216:219], v[178:181], v[34:37]
	v_mfma_f32_16x16x32_bf16 v[22:25], v[202:205], v[186:189], v[22:25]
	v_mfma_f32_16x16x32_bf16 v[18:21], v[216:219], v[186:189], v[18:21]
	v_mfma_f32_16x16x32_bf16 v[6:9], v[202:205], v[194:197], v[6:9]
	v_mfma_f32_16x16x32_bf16 v[2:5], v[216:219], v[194:197], v[2:5]
	s_setprio 0
	s_addk_i32 s27, 0x80
	s_add_u32 s42, s42, 0x100
	s_addc_u32 s43, s43, 0
	s_barrier
	s_cbranch_vccz .LBB0_375
	s_add_i32 s15, s26, s22
	s_ashr_i32 s29, s15, 5
	s_cmp_gt_i32 s29, 63
	s_cselect_b64 s[26:27], -1, 0
	v_mov_b32_e32 v149, v145
	v_mov_b32_e32 v150, v146
	s_and_b64 vcc, exec, s[26:27]
	s_cbranch_vccz .LBB0_378
	v_mul_f32_e32 v151, 0xbfb8aa3b, v122
	v_exp_f32_e32 v151, v151
	v_mul_f32_e32 v152, 0xbfb8aa3b, v123
	v_mul_f32_e32 v153, 0xbfb8aa3b, v124
	v_exp_f32_e32 v154, v152
	v_add_f32_e32 v151, 1.0, v151
	v_rcp_f32_e32 v152, v151
	v_exp_f32_e32 v151, v153
	v_mul_f32_e32 v153, 0xbfb8aa3b, v125
	v_exp_f32_e32 v153, v153
	v_add_f32_e32 v156, 1.0, v154
	v_add_f32_e32 v151, 1.0, v151
	v_rcp_f32_e32 v154, v151
	v_add_f32_e32 v151, 1.0, v153
	v_rcp_f32_e32 v155, v151
	v_rcp_f32_e32 v153, v156
	v_pk_mul_f32 v[124:125], v[124:125], v[154:155]
	v_pk_mul_f32 v[122:123], v[122:123], v[152:153]
